# combo10: combo9 + EpiUp broadcast operands: per-row rs scalars selected with op_sel inside their aligned register pair instead of v_mov broadcast pairs (62 fewer VALU per unit)
# speedup vs baseline: 1.0083x; 1.0027x over previous
; #define PG8_LAS __attribute__((address_space(3)))
;     __device__ __forceinline__ void run(const f32x4 (&acc)[2][2][4][2], const Unit& u, const Unit& nxt, bool has_next, int ui, int wr, int wc, int fr_in, int fq_in) const {
;     ...
;         float* eg = edge + (size_t)(u.pm * 22 + u.pn) * 1024;
;         float rs[2][4];
; #pragma unroll
;         for (int ai = 0; ai < 2; ++ai)
; #pragma unroll
;             for (int m = 0; m < 4; ++m) rs[ai][m] = rsd[slot * 256 + ai * 128 + wr * 64 + 4 * fr + m];
; #pragma unroll
;         for (int bj = 0; bj < 2; ++bj)
; #pragma unroll
;             for (int n = 0; n < 2; ++n) {
;                 const int colt = bj * 128 + wc * 32 + n * 16 + 4 * fq;
;                 if (fr == 15) {
;                     *(PG8_LAS f32x4*)(xr + ((0 + wr) * 2 + 0) * 256 + colt) = acc[0][bj][2][n] * rs[0][2]; *(PG8_LAS f32x4*)(xr + ((0 + wr) * 2 + 1) * 256 + colt) = acc[0][bj][3][n] * rs[0][3];
;                     *(PG8_LAS f32x4*)(xr + ((2 + wr) * 2 + 0) * 256 + colt) = acc[1][bj][2][n] * rs[1][2]; *(PG8_LAS f32x4*)(xr + ((2 + wr) * 2 + 1) * 256 + colt) = acc[1][bj][3][n] * rs[1][3];
;                     if (wr == 1) { *(f32x4*)(eg + 2 * 256 + colt) = acc[1][bj][2][n] * rs[1][2]; *(f32x4*)(eg + 3 * 256 + colt) = acc[1][bj][3][n] * rs[1][3]; }
;                 }
;                 if (wr == 0 && fr == 0) { *(f32x4*)(eg + colt) = acc[0][bj][0][n] * rs[0][0]; *(f32x4*)(eg + 256 + colt) = acc[0][bj][1][n] * rs[0][1]; }
;             }
.LBB0_697:
	s_and_b32 s37, s16, 1
	s_lshl_b32 s35, s37, 10
	s_add_i32 s4, s69, s35
	v_lshl_add_u32 v72, v169, 4, s4
	s_mul_i32 s0, s42, 22
	ds_read_b128 v[100:103], v72
	ds_read_b128 v[72:75], v72 offset:512
	s_add_i32 s0, s0, s44
	s_ashr_i32 s1, s0, 31
	s_lshl_b64 s[0:1], s[0:1], 12
	s_add_u32 s4, s55, s0
	v_lshl_add_u32 v202, v136, 2, s58
	v_cndmask_b32_e64 v136, 0, 1, s[18:19]
	s_addc_u32 s5, s56, s1
	v_cmp_eq_u32_e64 s[16:17], 15, v169
	s_waitcnt lgkmcnt(0)
	v_lshl_add_u32 v230, v202, 2, s70
	v_cmp_ne_u32_e64 s[12:13], 1, v136
	s_and_saveexec_b64 s[0:1], s[16:17]
	s_cbranch_execz .LBB0_700
	v_pk_mul_f32 v[138:139], v[118:119], v[102:103] op_sel_hi:[1,0]
	v_pk_mul_f32 v[136:137], v[116:117], v[102:103] op_sel_hi:[1,0]
	ds_write_b128 v230, v[136:139]
	v_pk_mul_f32 v[138:139], v[110:111], v[102:103] op_sel:[0,1]
	v_pk_mul_f32 v[136:137], v[108:109], v[102:103] op_sel:[0,1]
	ds_write_b128 v230, v[136:139] offset:1024
	v_pk_mul_f32 v[138:139], v[82:83], v[74:75] op_sel_hi:[1,0]
	v_pk_mul_f32 v[136:137], v[80:81], v[74:75] op_sel_hi:[1,0]
	v_pk_mul_f32 v[142:143], v[70:71], v[74:75] op_sel:[0,1]
	v_pk_mul_f32 v[140:141], v[68:69], v[74:75] op_sel:[0,1]
	s_and_b64 vcc, exec, s[12:13]
	ds_write_b128 v230, v[136:139] offset:4096
	ds_write_b128 v230, v[140:143] offset:5120
	s_cbranch_vccnz .LBB0_700
	v_ashrrev_i32_e32 v203, 31, v202
	v_lshl_add_u64 v[152:153], v[202:203], 2, s[4:5]
	global_store_dwordx4 v[152:153], v[136:139], off offset:2048
	global_store_dwordx4 v[152:153], v[140:143], off offset:3072
.LBB0_700:
	s_or_b64 exec, exec, s[0:1]
	v_cmp_eq_u32_e64 s[14:15], 0, v169
	s_and_b64 s[46:47], s[26:27], s[14:15]
	v_ashrrev_i32_e32 v203, 31, v202
	s_and_saveexec_b64 s[0:1], s[46:47]
	s_cbranch_execz .LBB0_702
	v_pk_mul_f32 v[138:139], v[134:135], v[100:101] op_sel_hi:[1,0]
	v_pk_mul_f32 v[136:137], v[132:133], v[100:101] op_sel_hi:[1,0]
	v_lshl_add_u64 v[156:157], v[202:203], 2, s[4:5]
	v_pk_mul_f32 v[142:143], v[126:127], v[100:101] op_sel:[0,1]
	v_pk_mul_f32 v[140:141], v[124:125], v[100:101] op_sel:[0,1]
	global_store_dwordx4 v[156:157], v[136:139], off
	global_store_dwordx4 v[156:157], v[140:143], off offset:1024
.LBB0_702:
	s_or_b64 exec, exec, s[0:1]
	s_and_saveexec_b64 s[0:1], s[16:17]
	s_cbranch_execz .LBB0_705
	v_pk_mul_f32 v[138:139], v[46:47], v[102:103] op_sel_hi:[1,0]
	v_pk_mul_f32 v[136:137], v[44:45], v[102:103] op_sel_hi:[1,0]
	ds_write_b128 v230, v[136:139] offset:64
	v_pk_mul_f32 v[138:139], v[38:39], v[102:103] op_sel:[0,1]
	v_pk_mul_f32 v[136:137], v[36:37], v[102:103] op_sel:[0,1]
	ds_write_b128 v230, v[136:139] offset:1088
	v_pk_mul_f32 v[138:139], v[14:15], v[74:75] op_sel_hi:[1,0]
	v_pk_mul_f32 v[136:137], v[12:13], v[74:75] op_sel_hi:[1,0]
	v_pk_mul_f32 v[142:143], v[6:7], v[74:75] op_sel:[0,1]
	v_pk_mul_f32 v[140:141], v[4:5], v[74:75] op_sel:[0,1]
	s_and_b64 vcc, exec, s[12:13]
	ds_write_b128 v230, v[136:139] offset:4160
	ds_write_b128 v230, v[140:143] offset:5184
	s_cbranch_vccnz .LBB0_705
	v_lshl_add_u64 v[156:157], v[202:203], 2, s[4:5]
	global_store_dwordx4 v[156:157], v[136:139], off offset:2112
	global_store_dwordx4 v[156:157], v[140:143], off offset:3136
.LBB0_705:
	s_or_b64 exec, exec, s[0:1]
	s_and_saveexec_b64 s[0:1], s[46:47]
	s_cbranch_execz .LBB0_707
	v_pk_mul_f32 v[138:139], v[62:63], v[100:101] op_sel_hi:[1,0]
	v_pk_mul_f32 v[136:137], v[60:61], v[100:101] op_sel_hi:[1,0]
	v_lshl_add_u64 v[156:157], v[202:203], 2, s[4:5]
	v_pk_mul_f32 v[142:143], v[54:55], v[100:101] op_sel:[0,1]
	v_pk_mul_f32 v[140:141], v[52:53], v[100:101] op_sel:[0,1]
	global_store_dwordx4 v[156:157], v[136:139], off offset:64
	global_store_dwordx4 v[156:157], v[140:143], off offset:1088
.LBB0_707:
	s_or_b64 exec, exec, s[0:1]
	s_and_saveexec_b64 s[0:1], s[16:17]
	s_cbranch_execz .LBB0_710
	v_pk_mul_f32 v[138:139], v[114:115], v[102:103] op_sel_hi:[1,0]
	v_pk_mul_f32 v[136:137], v[112:113], v[102:103] op_sel_hi:[1,0]
	ds_write_b128 v230, v[136:139] offset:512
	v_pk_mul_f32 v[138:139], v[106:107], v[102:103] op_sel:[0,1]
	v_pk_mul_f32 v[136:137], v[104:105], v[102:103] op_sel:[0,1]
	ds_write_b128 v230, v[136:139] offset:1536
	v_pk_mul_f32 v[138:139], v[78:79], v[74:75] op_sel_hi:[1,0]
	v_pk_mul_f32 v[136:137], v[76:77], v[74:75] op_sel_hi:[1,0]
	v_pk_mul_f32 v[142:143], v[66:67], v[74:75] op_sel:[0,1]
	v_pk_mul_f32 v[140:141], v[64:65], v[74:75] op_sel:[0,1]
	s_and_b64 vcc, exec, s[12:13]
	ds_write_b128 v230, v[136:139] offset:4608
	ds_write_b128 v230, v[140:143] offset:5632
	s_cbranch_vccnz .LBB0_710
	v_lshl_add_u64 v[156:157], v[202:203], 2, s[4:5]
	global_store_dwordx4 v[156:157], v[136:139], off offset:2560
	global_store_dwordx4 v[156:157], v[140:143], off offset:3584
.LBB0_710:
	s_or_b64 exec, exec, s[0:1]
	s_and_saveexec_b64 s[0:1], s[46:47]
	s_cbranch_execz .LBB0_712
	v_pk_mul_f32 v[138:139], v[130:131], v[100:101] op_sel_hi:[1,0]
	v_pk_mul_f32 v[136:137], v[128:129], v[100:101] op_sel_hi:[1,0]
	v_lshl_add_u64 v[156:157], v[202:203], 2, s[4:5]
	v_pk_mul_f32 v[142:143], v[122:123], v[100:101] op_sel:[0,1]
	v_pk_mul_f32 v[140:141], v[120:121], v[100:101] op_sel:[0,1]
	global_store_dwordx4 v[156:157], v[136:139], off offset:512
	global_store_dwordx4 v[156:157], v[140:143], off offset:1536
.LBB0_712:
	s_or_b64 exec, exec, s[0:1]
	s_and_saveexec_b64 s[0:1], s[16:17]
	s_cbranch_execz .LBB0_715
	v_pk_mul_f32 v[138:139], v[42:43], v[102:103] op_sel_hi:[1,0]
	v_pk_mul_f32 v[136:137], v[40:41], v[102:103] op_sel_hi:[1,0]
	ds_write_b128 v230, v[136:139] offset:576
	v_pk_mul_f32 v[138:139], v[34:35], v[102:103] op_sel:[0,1]
	v_pk_mul_f32 v[136:137], v[32:33], v[102:103] op_sel:[0,1]
	ds_write_b128 v230, v[136:139] offset:1600
	v_pk_mul_f32 v[138:139], v[10:11], v[74:75] op_sel_hi:[1,0]
	v_pk_mul_f32 v[136:137], v[8:9], v[74:75] op_sel_hi:[1,0]
	v_pk_mul_f32 v[142:143], v[2:3], v[74:75] op_sel:[0,1]
	v_pk_mul_f32 v[140:141], v[0:1], v[74:75] op_sel:[0,1]
	s_and_b64 vcc, exec, s[12:13]
	ds_write_b128 v230, v[136:139] offset:4672
	ds_write_b128 v230, v[140:143] offset:5696
	s_cbranch_vccnz .LBB0_715
	v_lshl_add_u64 v[144:145], v[202:203], 2, s[4:5]
	global_store_dwordx4 v[144:145], v[136:139], off offset:2624
	global_store_dwordx4 v[144:145], v[140:143], off offset:3648
.LBB0_715:
	s_or_b64 exec, exec, s[0:1]
	s_and_saveexec_b64 s[0:1], s[46:47]
	s_cbranch_execz .LBB0_717
	v_pk_mul_f32 v[138:139], v[58:59], v[100:101] op_sel_hi:[1,0]
	v_pk_mul_f32 v[136:137], v[56:57], v[100:101] op_sel_hi:[1,0]
	v_lshl_add_u64 v[144:145], v[202:203], 2, s[4:5]
	v_pk_mul_f32 v[142:143], v[50:51], v[100:101] op_sel:[0,1]
	v_pk_mul_f32 v[140:141], v[48:49], v[100:101] op_sel:[0,1]
	global_store_dwordx4 v[144:145], v[136:139], off offset:576
	global_store_dwordx4 v[144:145], v[140:143], off offset:1600

; __device__ __forceinline__ unsigned pk2(float lo, float hi) { f32x2_t v = {lo, hi}; bf16x2_t b = __builtin_convertvector(v, bf16x2_t); return __builtin_bit_cast(unsigned, b); }
; #define DPPF(v, ctrl) __builtin_bit_cast(float, __builtin_amdgcn_update_dpp(0, __builtin_bit_cast(int, (v)), (ctrl), 0xf, 0xf, false))
; __device__ __forceinline__ float sigmoidf_(float v) { return fast_rcp(1.0f + fast_exp2(-v * LOG2E)); }
;     __device__ __forceinline__ void run(const f32x4 (&acc)[2][2][4][2], const Unit& u, const Unit& nxt, bool has_next, int ui, int wr, int wc, int fr_in, int fq_in) const {
;     ...
;                     const f32x4 g2 = acc[ai][0][2][n] * rs[ai][2], g3 = acc[ai][0][3][n] * rs[ai][3], v2 = acc[ai][1][2][n] * rs[ai][2], v3 = acc[ai][1][3][n] * rs[ai][3];
; #pragma unroll
;                     for (int i = 0; i < 4; ++i) {
;                         float a0 = g2[i], a1 = g3[i], a2 = v2[i], a3 = v3[i];
;                         asm volatile("" : "+v"(a0), "+v"(a1), "+v"(a2), "+v"(a3));
;                         const float t0 = DPPF(a0, 0x111), t1 = DPPF(a1, 0x111), t2 = DPPF(a2, 0x111), t3 = DPPF(a3, 0x111);
;                         pg2[i] = t0 + hg2[i]; pg1[i] = t1 + hg3[i]; pv2[i] = t2 + hv2[i]; pv1[i] = t3 + hv3[i]; }
;                 }
; #pragma unroll
;                 for (int m = 0; m < 4; ++m) {
;                     const f32x4 gc = acc[ai][0][m][n] * rs[ai][m], vc = acc[ai][1][m][n] * rs[ai][m];
;                     const f32x4 cgt = bg + wg0 * pg2 + wg1 * pg1 + wg2 * gc, cvl = bv + wv0 * pv2 + wv1 * pv1 + wv2 * vc;
;                     float a[4];
; #pragma unroll
;                     for (int i = 0; i < 4; ++i) a[i] = cgt[i] * sigmoidf_(cgt[i]) * cvl[i];
;                     u32x2 w; w.x = pk2(a[0], a[1]); w.y = pk2(a[2], a[3]);
;                     *(u32x2*)(A + (size_t)(u.pm * BM + ai * 128 + wr * 64 + 4 * fr + m) * DFF + ch) = w;
.LBB0_723:
	s_or_b64 exec, exec, s[0:1]
	v_mul_f32_dpp v146, v44, v198 row_shr:1 row_mask:0xf bank_mask:0xf bound_ctrl:1
	s_nop 0
	v_mul_f32_dpp v152, v32, v199 row_shr:1 row_mask:0xf bank_mask:0xf bound_ctrl:1
	v_mul_f32_dpp v150, v40, v198 row_shr:1 row_mask:0xf bank_mask:0xf bound_ctrl:1
	v_mul_f32_dpp v148, v36, v199 row_shr:1 row_mask:0xf bank_mask:0xf bound_ctrl:1
	v_mul_f32_dpp v149, v37, v199 row_shr:1 row_mask:0xf bank_mask:0xf bound_ctrl:1
	v_mul_f32_dpp v147, v45, v198 row_shr:1 row_mask:0xf bank_mask:0xf bound_ctrl:1
	v_mul_f32_dpp v151, v41, v198 row_shr:1 row_mask:0xf bank_mask:0xf bound_ctrl:1
	v_mul_f32_dpp v153, v33, v199 row_shr:1 row_mask:0xf bank_mask:0xf bound_ctrl:1
	v_mul_f32_dpp v154, v46, v198 row_shr:1 row_mask:0xf bank_mask:0xf bound_ctrl:1
	v_mul_f32_dpp v160, v34, v199 row_shr:1 row_mask:0xf bank_mask:0xf bound_ctrl:1
	s_waitcnt lgkmcnt(0)
	v_pk_add_f32 v[118:119], v[118:119], v[146:147]
	v_mov_b32_e32 v140, v100
	v_mov_b32_e32 v141, v100
	v_mul_f32_dpp v158, v42, v198 row_shr:1 row_mask:0xf bank_mask:0xf bound_ctrl:1
	v_pk_add_f32 v[114:115], v[114:115], v[148:149]
	v_pk_fma_f32 v[118:119], v[84:85], v[118:119], v[96:97]
	v_mul_f32_dpp v157, v39, v199 row_shr:1 row_mask:0xf bank_mask:0xf bound_ctrl:1
	v_pk_mul_f32 v[60:61], v[60:61], v[100:101] op_sel_hi:[1,0]
	v_pk_fma_f32 v[118:119], v[88:89], v[114:115], v[118:119]
	v_mul_f32_dpp v159, v43, v198 row_shr:1 row_mask:0xf bank_mask:0xf bound_ctrl:1
	v_pk_fma_f32 v[118:119], v[60:61], v[92:93], v[118:119]
	v_mul_f32_dpp v156, v38, v199 row_shr:1 row_mask:0xf bank_mask:0xf bound_ctrl:1
	v_mul_f32_dpp v161, v35, v199 row_shr:1 row_mask:0xf bank_mask:0xf bound_ctrl:1
	v_mov_b32_e32 v162, v100
	v_mov_b32_e32 v163, v100
	v_mul_f32_dpp v155, v47, v198 row_shr:1 row_mask:0xf bank_mask:0xf bound_ctrl:1
	v_exp_f32_e32 v100, v118
	v_exp_f32_e32 v105, v119
	v_pk_mul_f32 v[140:141], v[56:57], v[140:141]
	v_add_f32_e32 v100, 1.0, v100
	v_rcp_f32_e32 v146, v100
	v_add_f32_e32 v100, 1.0, v105
	v_rcp_f32_e32 v147, v100
	v_pk_add_f32 v[56:57], v[110:111], v[150:151]
	v_pk_add_f32 v[116:117], v[116:117], v[156:157]
	v_pk_mul_f32 v[62:63], v[62:63], v[162:163]
	v_pk_mul_f32 v[110:111], v[118:119], v[146:147]
	v_pk_add_f32 v[118:119], v[120:121], v[154:155]
	v_pk_add_f32 v[106:107], v[106:107], v[152:153]
	v_pk_fma_f32 v[118:119], v[86:87], v[118:119], v[98:99]
	v_pk_fma_f32 v[56:57], v[64:65], v[56:57], v[80:81]
	v_pk_fma_f32 v[118:119], v[90:91], v[116:117], v[118:119]
	v_pk_fma_f32 v[56:57], v[68:69], v[106:107], v[56:57]
	v_pk_fma_f32 v[118:119], v[62:63], v[94:95], v[118:119]
	v_pk_fma_f32 v[56:57], v[140:141], v[76:77], v[56:57]
	v_exp_f32_e32 v100, v118
	v_exp_f32_e32 v105, v119
	v_pk_mul_f32 v[56:57], v[56:57], v[110:111]
	v_add_f32_e32 v100, 1.0, v100
	v_rcp_f32_e32 v120, v100
	v_add_f32_e32 v100, 1.0, v105
	v_rcp_f32_e32 v121, v100
	v_pk_add_f32 v[110:111], v[112:113], v[158:159]
	v_pk_add_f32 v[108:109], v[108:109], v[160:161]
	v_pk_fma_f32 v[110:111], v[66:67], v[110:111], v[82:83]
	v_add_u32_e32 v144, s16, v176
	v_pk_mul_f32 v[58:59], v[58:59], v[162:163]
	v_pk_fma_f32 v[110:111], v[70:71], v[108:109], v[110:111]
	v_ashrrev_i32_e32 v145, 31, v144
	v_pk_mul_f32 v[112:113], v[118:119], v[120:121]
	v_pk_fma_f32 v[110:111], v[58:59], v[78:79], v[110:111]
	v_mov_b32_e32 v142, v101
	v_pk_mul_f32 v[110:111], v[110:111], v[112:113]
	v_cvt_pk_bf16_f32 v112, v56, v57
	v_lshlrev_b64 v[56:57], 1, v[144:145]
	v_cvt_pk_bf16_f32 v113, v110, v111
	v_lshl_add_u64 v[110:111], v[128:129], 0, v[56:57]
	v_mov_b32_e32 v143, v101
	global_store_dwordx2 v[110:111], v[112:113], off
	v_pk_fma_f32 v[110:111], v[84:85], v[114:115], v[96:97]
	v_pk_mul_f32 v[52:53], v[52:53], v[142:143]
	v_pk_fma_f32 v[110:111], v[60:61], v[88:89], v[110:111]
	v_pk_fma_f32 v[106:107], v[64:65], v[106:107], v[80:81]
	v_pk_fma_f32 v[110:111], v[52:53], v[92:93], v[110:111]
	v_pk_mul_f32 v[48:49], v[48:49], v[142:143]
	v_exp_f32_e32 v105, v110
	v_exp_f32_e32 v113, v111
	v_mov_b32_e32 v100, v101
	v_add_f32_e32 v105, 1.0, v105
	v_rcp_f32_e32 v112, v105
	v_add_f32_e32 v105, 1.0, v113
	v_rcp_f32_e32 v113, v105
	v_pk_mul_f32 v[54:55], v[54:55], v[100:101]
	v_pk_mul_f32 v[50:51], v[50:51], v[100:101]
	v_pk_fma_f32 v[106:107], v[140:141], v[68:69], v[106:107]
	v_pk_mul_f32 v[100:101], v[110:111], v[112:113]
	v_pk_fma_f32 v[110:111], v[86:87], v[116:117], v[98:99]
	v_pk_fma_f32 v[108:109], v[66:67], v[108:109], v[82:83]
	v_pk_fma_f32 v[110:111], v[62:63], v[90:91], v[110:111]
	v_pk_fma_f32 v[106:107], v[48:49], v[76:77], v[106:107]
	v_pk_fma_f32 v[110:111], v[54:55], v[94:95], v[110:111]
	v_pk_fma_f32 v[108:109], v[58:59], v[70:71], v[108:109]
	v_exp_f32_e32 v105, v110
	v_exp_f32_e32 v113, v111
	v_mov_b32_e32 v138, v102
	v_add_f32_e32 v105, 1.0, v105
	v_rcp_f32_e32 v112, v105
	v_add_f32_e32 v105, 1.0, v113
	v_rcp_f32_e32 v113, v105
	v_mov_b32_e32 v139, v102
	v_pk_mul_f32 v[100:101], v[106:107], v[100:101]
	v_pk_fma_f32 v[108:109], v[50:51], v[78:79], v[108:109]
	v_pk_mul_f32 v[106:107], v[110:111], v[112:113]
	v_pk_fma_f32 v[60:61], v[60:61], v[84:85], v[96:97]
	v_pk_mul_f32 v[106:107], v[108:109], v[106:107]
	v_pk_mul_f32 v[44:45], v[44:45], v[138:139]
	v_pk_fma_f32 v[60:61], v[52:53], v[88:89], v[60:61]
	v_cvt_pk_bf16_f32 v100, v100, v101
	v_cvt_pk_bf16_f32 v101, v106, v107
	v_lshl_add_u64 v[106:107], v[126:127], 0, v[56:57]
	v_pk_fma_f32 v[60:61], v[44:45], v[92:93], v[60:61]
	v_mov_b32_e32 v136, v103
	v_mov_b32_e32 v137, v103
	global_store_dwordx2 v[106:107], v[100:101], off
	v_pk_fma_f32 v[52:53], v[52:53], v[84:85], v[96:97]
	v_exp_f32_e32 v105, v60
	v_pk_mul_f32 v[36:37], v[36:37], v[102:103] op_sel:[0,1]
; __device__ __forceinline__ unsigned pk2(float lo, float hi) { f32x2_t v = {lo, hi}; bf16x2_t b = __builtin_convertvector(v, bf16x2_t); return __builtin_bit_cast(unsigned, b); }
; #define DPPF(v, ctrl) __builtin_bit_cast(float, __builtin_amdgcn_update_dpp(0, __builtin_bit_cast(int, (v)), (ctrl), 0xf, 0xf, false))
; __device__ __forceinline__ float sigmoidf_(float v) { return fast_rcp(1.0f + fast_exp2(-v * LOG2E)); }
; #define PG8_LAS __attribute__((address_space(3)))
;     __device__ __forceinline__ void run(const f32x4 (&acc)[2][2][4][2], const Unit& u, const Unit& nxt, bool has_next, int ui, int wr, int wc, int fr_in, int fq_in) const {
;     ...
;                 if (grp > 0 && fr == 0) { const PG8_LAS float* xp = xr + ((grp - 1) * 2) * 256 + cl;
;                     hg2 = *(const PG8_LAS f32x4*)(xp); hg3 = *(const PG8_LAS f32x4*)(xp + 256); hv2 = *(const PG8_LAS f32x4*)(xp + 128); hv3 = *(const PG8_LAS f32x4*)(xp + 256 + 128); }
;                 f32x4 pg2, pg1, pv2, pv1;
;                 {
;                     const f32x4 g2 = acc[ai][0][2][n] * rs[ai][2], g3 = acc[ai][0][3][n] * rs[ai][3], v2 = acc[ai][1][2][n] * rs[ai][2], v3 = acc[ai][1][3][n] * rs[ai][3];
; #pragma unroll
;                     for (int i = 0; i < 4; ++i) {
;                         float a0 = g2[i], a1 = g3[i], a2 = v2[i], a3 = v3[i];
;                         asm volatile("" : "+v"(a0), "+v"(a1), "+v"(a2), "+v"(a3));
;                         const float t0 = DPPF(a0, 0x111), t1 = DPPF(a1, 0x111), t2 = DPPF(a2, 0x111), t3 = DPPF(a3, 0x111);
;                         pg2[i] = t0 + hg2[i]; pg1[i] = t1 + hg3[i]; pv2[i] = t2 + hv2[i]; pv1[i] = t3 + hv3[i]; }
;                 }
; #pragma unroll
;                 for (int m = 0; m < 4; ++m) {
;                     const f32x4 gc = acc[ai][0][m][n] * rs[ai][m], vc = acc[ai][1][m][n] * rs[ai][m];
;                     const f32x4 cgt = bg + wg0 * pg2 + wg1 * pg1 + wg2 * gc, cvl = bv + wv0 * pv2 + wv1 * pv1 + wv2 * vc;
;                     float a[4];
; #pragma unroll
;                     for (int i = 0; i < 4; ++i) a[i] = cgt[i] * sigmoidf_(cgt[i]) * cvl[i];
;                     u32x2 w; w.x = pk2(a[0], a[1]); w.y = pk2(a[2], a[3]);
;                     *(u32x2*)(A + (size_t)(u.pm * BM + ai * 128 + wr * 64 + 4 * fr + m) * DFF + ch) = w;
	v_pk_fma_f32 v[44:45], v[44:45], v[88:89], v[52:53]
	v_exp_f32_e32 v107, v61
	v_pk_fma_f32 v[36:37], v[36:37], v[92:93], v[44:45]
	v_mov_b32_e32 v100, v102
	v_mov_b32_e32 v101, v102
	v_pk_fma_f32 v[62:63], v[62:63], v[86:87], v[98:99]
	v_pk_mul_f32 v[46:47], v[46:47], v[102:103] op_sel_hi:[1,0]
	v_pk_fma_f32 v[62:63], v[54:55], v[90:91], v[62:63]
	v_exp_f32_e32 v44, v36
	v_exp_f32_e32 v45, v37
	v_add_f32_e32 v102, 1.0, v105
	v_pk_fma_f32 v[62:63], v[46:47], v[94:95], v[62:63]
	v_rcp_f32_e32 v106, v102
	v_add_f32_e32 v102, 1.0, v107
	v_pk_mul_f32 v[42:43], v[42:43], v[100:101]
	v_rcp_f32_e32 v107, v102
	v_exp_f32_e32 v102, v62
	v_exp_f32_e32 v105, v63
	v_add_f32_e32 v44, 1.0, v44
	v_add_f32_e32 v45, 1.0, v45
	v_rcp_f32_e32 v44, v44
	v_rcp_f32_e32 v45, v45
	v_add_f32_e32 v102, 1.0, v102
	v_pk_mul_f32 v[60:61], v[60:61], v[106:107]
	v_rcp_f32_e32 v106, v102
	v_add_f32_e32 v102, 1.0, v105
	v_rcp_f32_e32 v107, v102
	v_mov_b32_e32 v102, v103
	v_pk_mul_f32 v[36:37], v[36:37], v[44:45]
	v_pk_fma_f32 v[44:45], v[54:55], v[86:87], v[98:99]
	v_pk_mul_f32 v[38:39], v[38:39], v[102:103]
	v_pk_fma_f32 v[44:45], v[46:47], v[90:91], v[44:45]
	v_pk_fma_f32 v[100:101], v[140:141], v[64:65], v[80:81]
	v_pk_fma_f32 v[38:39], v[38:39], v[94:95], v[44:45]
	v_pk_mul_f32 v[40:41], v[40:41], v[138:139]
	v_exp_f32_e32 v46, v38
	v_exp_f32_e32 v47, v39
	v_pk_fma_f32 v[100:101], v[48:49], v[68:69], v[100:101]
	v_add_f32_e32 v46, 1.0, v46
	v_rcp_f32_e32 v46, v46
	v_add_f32_e32 v47, 1.0, v47
	v_rcp_f32_e32 v47, v47
	v_pk_fma_f32 v[44:45], v[48:49], v[64:65], v[80:81]
	v_pk_fma_f32 v[100:101], v[40:41], v[76:77], v[100:101]
	v_pk_mul_f32 v[32:33], v[32:33], v[102:103] op_sel:[0,1]
	v_pk_fma_f32 v[40:41], v[40:41], v[68:69], v[44:45]
	v_pk_fma_f32 v[58:59], v[58:59], v[66:67], v[82:83]
	v_pk_fma_f32 v[32:33], v[32:33], v[76:77], v[40:41]
	v_pk_fma_f32 v[58:59], v[50:51], v[70:71], v[58:59]
	v_pk_mul_f32 v[32:33], v[32:33], v[36:37]
	v_pk_mul_f32 v[36:37], v[38:39], v[46:47]
	v_pk_fma_f32 v[38:39], v[50:51], v[66:67], v[82:83]
	v_pk_mul_f32 v[34:35], v[34:35], v[102:103]
	v_pk_fma_f32 v[38:39], v[42:43], v[70:71], v[38:39]
	v_pk_mul_f32 v[62:63], v[62:63], v[106:107]
	v_pk_fma_f32 v[58:59], v[42:43], v[78:79], v[58:59]
	v_pk_fma_f32 v[34:35], v[34:35], v[78:79], v[38:39]
	v_pk_mul_f32 v[60:61], v[100:101], v[60:61]
	v_pk_mul_f32 v[58:59], v[58:59], v[62:63]
	v_pk_mul_f32 v[34:35], v[34:35], v[36:37]
	v_cvt_pk_bf16_f32 v60, v60, v61
	v_cvt_pk_bf16_f32 v61, v58, v59
	v_lshl_add_u64 v[58:59], v[132:133], 0, v[56:57]
	v_cvt_pk_bf16_f32 v32, v32, v33
	v_cvt_pk_bf16_f32 v33, v34, v35
	v_lshl_add_u64 v[34:35], v[172:173], 0, v[56:57]
	global_store_dwordx2 v[58:59], v[60:61], off
	global_store_dwordx2 v[34:35], v[32:33], off
	v_mov_b32_e32 v105, 0
	v_mov_b32_e32 v106, 0
	v_mov_b32_e32 v107, 0
	v_mov_b32_e32 v32, 0
	v_mov_b32_e32 v33, 0
	v_mov_b32_e32 v34, 0
	v_mov_b32_e32 v35, 0
	v_mov_b32_e32 v36, 0
	v_mov_b32_e32 v37, 0
	v_mov_b32_e32 v38, 0
	v_mov_b32_e32 v39, 0
	v_mov_b32_e32 v40, 0
	v_mov_b32_e32 v41, 0
	v_mov_b32_e32 v42, 0
	v_mov_b32_e32 v43, 0
	s_and_saveexec_b64 s[0:1], s[14:15]
	s_cbranch_execz .LBB0_725
	ds_read_b128 v[40:43], v230 offset:2112
	ds_read_b128 v[32:35], v230 offset:2624
	ds_read_b128 v[36:39], v230 offset:3136
	ds_read_b128 v[104:107], v230 offset:3648
.LBB0_725:
	s_or_b64 exec, exec, s[0:1]
	v_mul_f32_dpp v54, v4, v201 row_shr:1 row_mask:0xf bank_mask:0xf bound_ctrl:1
	v_mul_f32_dpp v58, v8, v200 row_shr:1 row_mask:0xf bank_mask:0xf bound_ctrl:1
	v_mul_f32_dpp v60, v0, v201 row_shr:1 row_mask:0xf bank_mask:0xf bound_ctrl:1
	v_mul_f32_dpp v52, v12, v200 row_shr:1 row_mask:0xf bank_mask:0xf bound_ctrl:1
	v_mul_f32_dpp v53, v13, v200 row_shr:1 row_mask:0xf bank_mask:0xf bound_ctrl:1
	s_waitcnt lgkmcnt(0)
	v_pk_add_f32 v[40:41], v[40:41], v[52:53]
	v_pk_mul_f32 v[28:29], v[28:29], v[72:73] op_sel_hi:[1,0]
	v_mul_f32_dpp v55, v5, v201 row_shr:1 row_mask:0xf bank_mask:0xf bound_ctrl:1
	v_pk_add_f32 v[36:37], v[36:37], v[54:55]
	v_pk_fma_f32 v[40:41], v[84:85], v[40:41], v[96:97]
	v_pk_fma_f32 v[40:41], v[88:89], v[36:37], v[40:41]
	v_pk_fma_f32 v[40:41], v[28:29], v[92:93], v[40:41]
	v_mul_f32_dpp v59, v9, v200 row_shr:1 row_mask:0xf bank_mask:0xf bound_ctrl:1
	v_exp_f32_e32 v52, v40
	v_exp_f32_e32 v53, v41
	v_mul_f32_dpp v61, v1, v201 row_shr:1 row_mask:0xf bank_mask:0xf bound_ctrl:1
	v_mul_f32_dpp v100, v6, v201 row_shr:1 row_mask:0xf bank_mask:0xf bound_ctrl:1
	v_mul_f32_dpp v102, v10, v200 row_shr:1 row_mask:0xf bank_mask:0xf bound_ctrl:1
	v_mul_f32_dpp v108, v2, v201 row_shr:1 row_mask:0xf bank_mask:0xf bound_ctrl:1
	v_mul_f32_dpp v62, v14, v200 row_shr:1 row_mask:0xf bank_mask:0xf bound_ctrl:1
	v_add_f32_e32 v52, 1.0, v52
	v_add_f32_e32 v53, 1.0, v53
	v_mul_f32_dpp v63, v15, v200 row_shr:1 row_mask:0xf bank_mask:0xf bound_ctrl:1
	v_rcp_f32_e32 v52, v52
	v_rcp_f32_e32 v53, v53
	v_mul_f32_dpp v101, v7, v201 row_shr:1 row_mask:0xf bank_mask:0xf bound_ctrl:1
	v_pk_add_f32 v[42:43], v[42:43], v[62:63]
	v_mov_b32_e32 v111, v72
	v_mul_f32_dpp v103, v11, v200 row_shr:1 row_mask:0xf bank_mask:0xf bound_ctrl:1
	v_pk_add_f32 v[38:39], v[38:39], v[100:101]
	v_pk_fma_f32 v[42:43], v[86:87], v[42:43], v[98:99]
	v_mul_f32_dpp v109, v3, v201 row_shr:1 row_mask:0xf bank_mask:0xf bound_ctrl:1
	v_mov_b32_e32 v110, v72
	v_pk_mul_f32 v[30:31], v[30:31], v[110:111]
	v_pk_fma_f32 v[42:43], v[90:91], v[38:39], v[42:43]
	v_pk_mul_f32 v[40:41], v[40:41], v[52:53]
	v_pk_fma_f32 v[42:43], v[30:31], v[94:95], v[42:43]
	v_pk_add_f32 v[32:33], v[32:33], v[58:59]
	v_exp_f32_e32 v52, v42
	v_exp_f32_e32 v53, v43
	v_pk_mul_f32 v[24:25], v[24:25], v[72:73] op_sel_hi:[1,0]
; __device__ __forceinline__ unsigned pk2(float lo, float hi) { f32x2_t v = {lo, hi}; bf16x2_t b = __builtin_convertvector(v, bf16x2_t); return __builtin_bit_cast(unsigned, b); }
; #define DPPF(v, ctrl) __builtin_bit_cast(float, __builtin_amdgcn_update_dpp(0, __builtin_bit_cast(int, (v)), (ctrl), 0xf, 0xf, false))
; __device__ __forceinline__ float fast_rsq(float x) { return __builtin_amdgcn_rsqf(x); }
; __device__ __forceinline__ float sigmoidf_(float v) { return fast_rcp(1.0f + fast_exp2(-v * LOG2E)); }
;     __device__ __forceinline__ void run(const f32x4 (&acc)[2][2][4][2], const Unit& u, const Unit& nxt, bool has_next, int ui, int wr, int wc, int fr_in, int fq_in) const {
;     ...
;                     const f32x4 g2 = acc[ai][0][2][n] * rs[ai][2], g3 = acc[ai][0][3][n] * rs[ai][3], v2 = acc[ai][1][2][n] * rs[ai][2], v3 = acc[ai][1][3][n] * rs[ai][3];
; #pragma unroll
;                     for (int i = 0; i < 4; ++i) {
;                         float a0 = g2[i], a1 = g3[i], a2 = v2[i], a3 = v3[i];
;                         asm volatile("" : "+v"(a0), "+v"(a1), "+v"(a2), "+v"(a3));
;                         const float t0 = DPPF(a0, 0x111), t1 = DPPF(a1, 0x111), t2 = DPPF(a2, 0x111), t3 = DPPF(a3, 0x111);
;                         pg2[i] = t0 + hg2[i]; pg1[i] = t1 + hg3[i]; pv2[i] = t2 + hv2[i]; pv1[i] = t3 + hv3[i]; }
;                 }
; #pragma unroll
;                 for (int m = 0; m < 4; ++m) {
;                     const f32x4 gc = acc[ai][0][m][n] * rs[ai][m], vc = acc[ai][1][m][n] * rs[ai][m];
;                     const f32x4 cgt = bg + wg0 * pg2 + wg1 * pg1 + wg2 * gc, cvl = bv + wv0 * pv2 + wv1 * pv1 + wv2 * vc;
;                     float a[4];
; #pragma unroll
;                     for (int i = 0; i < 4; ++i) a[i] = cgt[i] * sigmoidf_(cgt[i]) * cvl[i];
;                     u32x2 w; w.x = pk2(a[0], a[1]); w.y = pk2(a[2], a[3]);
;                     *(u32x2*)(A + (size_t)(u.pm * BM + ai * 128 + wr * 64 + 4 * fr + m) * DFF + ch) = w;
;                     pg2 = pg1; pg1 = gc; pv2 = pv1; pv1 = vc;
;                 }
;                 asm volatile("" ::: "memory");
;             }
;         }
;         if (has_next) {
;             prm[(slot ^ 1) * 1024 + tid] = nx0; prm[(slot ^ 1) * 1024 + tid + 512] = nx1;
;             if (tid < 256) rsd[(slot ^ 1) * 256 + tid] = fast_rsq(nrs * (1.0f / DM) + EPS);
;         }
	v_pk_add_f32 v[48:49], v[104:105], v[60:61]
	v_pk_fma_f32 v[32:33], v[64:65], v[32:33], v[80:81]
	v_add_f32_e32 v52, 1.0, v52
	v_add_f32_e32 v53, 1.0, v53
	v_pk_fma_f32 v[32:33], v[68:69], v[48:49], v[32:33]
	v_rcp_f32_e32 v52, v52
	v_rcp_f32_e32 v53, v53
	v_pk_fma_f32 v[32:33], v[24:25], v[76:77], v[32:33]
	v_pk_add_f32 v[34:35], v[34:35], v[102:103]
	v_pk_mul_f32 v[32:33], v[32:33], v[40:41]
	v_pk_add_f32 v[40:41], v[106:107], v[108:109]
	v_pk_fma_f32 v[34:35], v[66:67], v[34:35], v[82:83]
	v_pk_mul_f32 v[26:27], v[26:27], v[110:111]
	v_pk_fma_f32 v[34:35], v[70:71], v[40:41], v[34:35]
	v_pk_mul_f32 v[42:43], v[42:43], v[52:53]
	v_pk_fma_f32 v[34:35], v[26:27], v[78:79], v[34:35]
	v_cvt_pk_bf16_f32 v32, v32, v33
	v_pk_mul_f32 v[34:35], v[34:35], v[42:43]
	v_mov_b32_e32 v50, v73
	v_cvt_pk_bf16_f32 v33, v34, v35
	v_lshl_add_u64 v[34:35], v[122:123], 0, v[56:57]
	v_mov_b32_e32 v51, v73
	global_store_dwordx2 v[34:35], v[32:33], off
	v_pk_fma_f32 v[32:33], v[84:85], v[36:37], v[96:97]
	v_pk_mul_f32 v[20:21], v[20:21], v[50:51]
	v_pk_fma_f32 v[32:33], v[28:29], v[88:89], v[32:33]
	v_mov_b32_e32 v72, v73
	v_pk_fma_f32 v[32:33], v[20:21], v[92:93], v[32:33]
	v_pk_mul_f32 v[22:23], v[22:23], v[72:73]
	v_exp_f32_e32 v34, v32
	v_exp_f32_e32 v35, v33
	v_mov_b32_e32 v46, v74
	v_mov_b32_e32 v47, v74
	v_add_f32_e32 v34, 1.0, v34
	v_add_f32_e32 v35, 1.0, v35
	v_rcp_f32_e32 v34, v34
	v_rcp_f32_e32 v35, v35
	v_pk_fma_f32 v[28:29], v[28:29], v[84:85], v[96:97]
	v_mov_b32_e32 v44, v75
	v_mov_b32_e32 v45, v75
	v_pk_mul_f32 v[32:33], v[32:33], v[34:35]
	v_pk_fma_f32 v[34:35], v[86:87], v[38:39], v[98:99]
	v_pk_mul_f32 v[12:13], v[12:13], v[74:75] op_sel_hi:[1,0]
	v_pk_fma_f32 v[34:35], v[30:31], v[90:91], v[34:35]
	v_pk_fma_f32 v[28:29], v[20:21], v[88:89], v[28:29]
	v_pk_fma_f32 v[34:35], v[22:23], v[94:95], v[34:35]
	v_pk_fma_f32 v[20:21], v[20:21], v[84:85], v[96:97]
	v_exp_f32_e32 v38, v34
	v_exp_f32_e32 v39, v35
	v_pk_fma_f32 v[28:29], v[12:13], v[92:93], v[28:29]
	v_pk_mul_f32 v[4:5], v[4:5], v[74:75] op_sel:[0,1]
	v_pk_fma_f32 v[12:13], v[12:13], v[88:89], v[20:21]
	v_pk_fma_f32 v[36:37], v[64:65], v[48:49], v[80:81]
	v_add_f32_e32 v38, 1.0, v38
	v_add_f32_e32 v39, 1.0, v39
	v_pk_fma_f32 v[4:5], v[4:5], v[92:93], v[12:13]
	v_pk_mul_f32 v[16:17], v[16:17], v[50:51]
	v_rcp_f32_e32 v38, v38
	v_rcp_f32_e32 v39, v39
	v_pk_fma_f32 v[36:37], v[24:25], v[68:69], v[36:37]
	v_pk_fma_f32 v[36:37], v[16:17], v[76:77], v[36:37]
	v_exp_f32_e32 v12, v4
	v_exp_f32_e32 v13, v5
	v_pk_mul_f32 v[32:33], v[36:37], v[32:33]
	v_pk_fma_f32 v[36:37], v[66:67], v[40:41], v[82:83]
	v_pk_mul_f32 v[18:19], v[18:19], v[72:73]
	v_pk_fma_f32 v[36:37], v[26:27], v[70:71], v[36:37]
	v_pk_mul_f32 v[34:35], v[34:35], v[38:39]
	v_pk_fma_f32 v[36:37], v[18:19], v[78:79], v[36:37]
	v_add_f32_e32 v12, 1.0, v12
	v_pk_mul_f32 v[34:35], v[36:37], v[34:35]
	v_add_f32_e32 v13, 1.0, v13
	v_cvt_pk_bf16_f32 v32, v32, v33
	v_cvt_pk_bf16_f32 v33, v34, v35
	v_lshl_add_u64 v[34:35], v[124:125], 0, v[56:57]
	v_rcp_f32_e32 v12, v12
	v_rcp_f32_e32 v13, v13
	global_store_dwordx2 v[34:35], v[32:33], off
	v_exp_f32_e32 v34, v28
	v_mov_b32_e32 v32, v74
	v_exp_f32_e32 v35, v29
	v_mov_b32_e32 v33, v74
	v_pk_mul_f32 v[14:15], v[14:15], v[32:33]
	v_mov_b32_e32 v74, v75
	v_pk_mul_f32 v[4:5], v[4:5], v[12:13]
	v_pk_fma_f32 v[12:13], v[22:23], v[86:87], v[98:99]
	v_pk_mul_f32 v[6:7], v[6:7], v[74:75]
	v_pk_fma_f32 v[12:13], v[14:15], v[90:91], v[12:13]
	v_pk_fma_f32 v[30:31], v[30:31], v[86:87], v[98:99]
	v_pk_fma_f32 v[6:7], v[6:7], v[94:95], v[12:13]
	v_pk_fma_f32 v[30:31], v[22:23], v[90:91], v[30:31]
	v_pk_fma_f32 v[30:31], v[14:15], v[94:95], v[30:31]
	v_exp_f32_e32 v14, v6
	v_exp_f32_e32 v15, v7
	v_pk_mul_f32 v[10:11], v[10:11], v[32:33]
	v_exp_f32_e32 v32, v30
	v_exp_f32_e32 v33, v31
	v_add_f32_e32 v14, 1.0, v14
	v_add_f32_e32 v15, 1.0, v15
	v_add_f32_e32 v34, 1.0, v34
	v_add_f32_e32 v35, 1.0, v35
	v_pk_fma_f32 v[24:25], v[24:25], v[64:65], v[80:81]
	v_rcp_f32_e32 v14, v14
	v_rcp_f32_e32 v15, v15
	v_rcp_f32_e32 v34, v34
	v_rcp_f32_e32 v35, v35
	v_pk_mul_f32 v[8:9], v[8:9], v[46:47]
	v_add_f32_e32 v32, 1.0, v32
	v_add_f32_e32 v33, 1.0, v33
	v_pk_fma_f32 v[24:25], v[16:17], v[68:69], v[24:25]
	v_pk_fma_f32 v[12:13], v[16:17], v[64:65], v[80:81]
	v_rcp_f32_e32 v32, v32
	v_rcp_f32_e32 v33, v33
	v_pk_fma_f32 v[24:25], v[8:9], v[76:77], v[24:25]
	v_pk_mul_f32 v[0:1], v[0:1], v[74:75] op_sel:[0,1]
	v_pk_fma_f32 v[8:9], v[8:9], v[68:69], v[12:13]
	v_pk_fma_f32 v[26:27], v[26:27], v[66:67], v[82:83]
	v_pk_fma_f32 v[0:1], v[0:1], v[76:77], v[8:9]
	v_pk_mul_f32 v[28:29], v[28:29], v[34:35]
	v_pk_mul_f32 v[0:1], v[0:1], v[4:5]
	v_pk_mul_f32 v[4:5], v[6:7], v[14:15]
	v_pk_fma_f32 v[6:7], v[18:19], v[66:67], v[82:83]
	v_pk_fma_f32 v[26:27], v[18:19], v[70:71], v[26:27]
	v_pk_mul_f32 v[2:3], v[2:3], v[74:75]
	v_pk_fma_f32 v[6:7], v[10:11], v[70:71], v[6:7]
	v_pk_mul_f32 v[24:25], v[24:25], v[28:29]
	v_pk_mul_f32 v[28:29], v[30:31], v[32:33]
	v_pk_fma_f32 v[26:27], v[10:11], v[78:79], v[26:27]
	v_pk_fma_f32 v[2:3], v[2:3], v[78:79], v[6:7]
	v_pk_mul_f32 v[26:27], v[26:27], v[28:29]
	v_pk_mul_f32 v[2:3], v[2:3], v[4:5]
	v_cvt_pk_bf16_f32 v24, v24, v25
	v_cvt_pk_bf16_f32 v25, v26, v27
	v_lshl_add_u64 v[26:27], v[130:131], 0, v[56:57]
	v_cvt_pk_bf16_f32 v0, v0, v1
	v_cvt_pk_bf16_f32 v1, v2, v3
	v_lshl_add_u64 v[2:3], v[134:135], 0, v[56:57]
	global_store_dwordx2 v[26:27], v[24:25], off
	global_store_dwordx2 v[2:3], v[0:1], off
	s_and_b64 vcc, exec, s[10:11]
	s_mov_b64 s[0:1], -1
	s_cbranch_vccnz .LBB0_681
	s_xor_b32 s4, s35, 0x400
	v_lshlrev_b32_e32 v0, 2, v226
	v_lshl_add_u32 v0, s4, 2, v0
	v_add_u32_e32 v0, 0x22040, v0
	v_cmp_gt_i32_e32 vcc, s65, v226
	s_waitcnt vmcnt(0)
	v_mul_f32_e32 v228, 0xbfb8aa3b, v228
	v_mul_f32_e32 v227, 0xbf317218, v227
	ds_write2st64_b32 v0, v228, v227 offset1:8
	s_and_saveexec_b64 s[0:1], vcc
	s_cbranch_execz .LBB0_728
	v_rsq_f32_e32 v0, v229
	v_lshl_add_u32 v1, v226, 2, s4
	v_add_u32_e32 v1, 0x24040, v1
	ds_write_b32 v1, v0

; #define PG8_LAS __attribute__((address_space(3)))
;     __device__ __forceinline__ void run(const f32x4 (&acc)[2][2][4][2], const Unit& u, const Unit& nxt, bool has_next, int ui, int wr, int wc, int fr_in, int fq_in) const {
;     ...
;         float* eg = edge + (size_t)(u.pm * 22 + u.pn) * 1024;
;         float rs[2][4];
; #pragma unroll
;         for (int ai = 0; ai < 2; ++ai)
; #pragma unroll
;             for (int m = 0; m < 4; ++m) rs[ai][m] = rsd[slot * 256 + ai * 128 + wr * 64 + 4 * fr + m];
; #pragma unroll
;         for (int bj = 0; bj < 2; ++bj)
; #pragma unroll
;             for (int n = 0; n < 2; ++n) {
;                 const int colt = bj * 128 + wc * 32 + n * 16 + 4 * fq;
;                 if (fr == 15) {
;                     *(PG8_LAS f32x4*)(xr + ((0 + wr) * 2 + 0) * 256 + colt) = acc[0][bj][2][n] * rs[0][2]; *(PG8_LAS f32x4*)(xr + ((0 + wr) * 2 + 1) * 256 + colt) = acc[0][bj][3][n] * rs[0][3];
;                     *(PG8_LAS f32x4*)(xr + ((2 + wr) * 2 + 0) * 256 + colt) = acc[1][bj][2][n] * rs[1][2]; *(PG8_LAS f32x4*)(xr + ((2 + wr) * 2 + 1) * 256 + colt) = acc[1][bj][3][n] * rs[1][3];
;                     if (wr == 1) { *(f32x4*)(eg + 2 * 256 + colt) = acc[1][bj][2][n] * rs[1][2]; *(f32x4*)(eg + 3 * 256 + colt) = acc[1][bj][3][n] * rs[1][3]; }
;                 }
;                 if (wr == 0 && fr == 0) { *(f32x4*)(eg + colt) = acc[0][bj][0][n] * rs[0][0]; *(f32x4*)(eg + 256 + colt) = acc[0][bj][1][n] * rs[0][1]; }
;             }
.LBB0_1559:
	s_and_b32 s31, s12, 1
	s_lshl_b32 s29, s31, 10
	s_add_i32 s4, s67, s29
	v_lshl_add_u32 v72, v169, 4, s4
	s_mul_i32 s0, s38, 22
	ds_read_b128 v[100:103], v72
	ds_read_b128 v[72:75], v72 offset:512
	s_add_i32 s0, s0, s40
	s_ashr_i32 s1, s0, 31
	s_lshl_b64 s[0:1], s[0:1], 12
	s_add_u32 s4, s56, s0
	v_lshl_add_u32 v202, v136, 2, s59
	v_cndmask_b32_e64 v136, 0, 1, s[14:15]
	s_addc_u32 s5, s57, s1
	v_cmp_eq_u32_e64 s[12:13], 15, v169
	s_waitcnt lgkmcnt(0)
	v_lshl_add_u32 v230, v202, 2, s68
	v_cmp_ne_u32_e64 s[8:9], 1, v136
	s_and_saveexec_b64 s[0:1], s[12:13]
	s_cbranch_execz .LBB0_1562
	v_pk_mul_f32 v[138:139], v[118:119], v[102:103] op_sel_hi:[1,0]
	v_pk_mul_f32 v[136:137], v[116:117], v[102:103] op_sel_hi:[1,0]
	ds_write_b128 v230, v[136:139]
	v_pk_mul_f32 v[138:139], v[110:111], v[102:103] op_sel:[0,1]
	v_pk_mul_f32 v[136:137], v[108:109], v[102:103] op_sel:[0,1]
	ds_write_b128 v230, v[136:139] offset:1024
	v_pk_mul_f32 v[138:139], v[82:83], v[74:75] op_sel_hi:[1,0]
	v_pk_mul_f32 v[136:137], v[80:81], v[74:75] op_sel_hi:[1,0]
	v_pk_mul_f32 v[142:143], v[70:71], v[74:75] op_sel:[0,1]
	v_pk_mul_f32 v[140:141], v[68:69], v[74:75] op_sel:[0,1]
	s_and_b64 vcc, exec, s[8:9]
	ds_write_b128 v230, v[136:139] offset:4096
	ds_write_b128 v230, v[140:143] offset:5120
	s_cbranch_vccnz .LBB0_1562
	v_ashrrev_i32_e32 v203, 31, v202
	v_lshl_add_u64 v[152:153], v[202:203], 2, s[4:5]
	global_store_dwordx4 v[152:153], v[136:139], off offset:2048
	global_store_dwordx4 v[152:153], v[140:143], off offset:3072
.LBB0_1562:
	s_or_b64 exec, exec, s[0:1]
	v_cmp_eq_u32_e64 s[10:11], 0, v169
	s_and_b64 s[42:43], s[22:23], s[10:11]
	v_ashrrev_i32_e32 v203, 31, v202
	s_and_saveexec_b64 s[0:1], s[42:43]
	s_cbranch_execz .LBB0_1564
	v_pk_mul_f32 v[138:139], v[134:135], v[100:101] op_sel_hi:[1,0]
	v_pk_mul_f32 v[136:137], v[132:133], v[100:101] op_sel_hi:[1,0]
	v_lshl_add_u64 v[156:157], v[202:203], 2, s[4:5]
	v_pk_mul_f32 v[142:143], v[126:127], v[100:101] op_sel:[0,1]
	v_pk_mul_f32 v[140:141], v[124:125], v[100:101] op_sel:[0,1]
	global_store_dwordx4 v[156:157], v[136:139], off
	global_store_dwordx4 v[156:157], v[140:143], off offset:1024
.LBB0_1564:
	s_or_b64 exec, exec, s[0:1]
	s_and_saveexec_b64 s[0:1], s[12:13]
	s_cbranch_execz .LBB0_1567
	v_pk_mul_f32 v[138:139], v[46:47], v[102:103] op_sel_hi:[1,0]
	v_pk_mul_f32 v[136:137], v[44:45], v[102:103] op_sel_hi:[1,0]
	ds_write_b128 v230, v[136:139] offset:64
	v_pk_mul_f32 v[138:139], v[38:39], v[102:103] op_sel:[0,1]
	v_pk_mul_f32 v[136:137], v[36:37], v[102:103] op_sel:[0,1]
	ds_write_b128 v230, v[136:139] offset:1088
	v_pk_mul_f32 v[138:139], v[14:15], v[74:75] op_sel_hi:[1,0]
	v_pk_mul_f32 v[136:137], v[12:13], v[74:75] op_sel_hi:[1,0]
	v_pk_mul_f32 v[142:143], v[6:7], v[74:75] op_sel:[0,1]
	v_pk_mul_f32 v[140:141], v[4:5], v[74:75] op_sel:[0,1]
	s_and_b64 vcc, exec, s[8:9]
	ds_write_b128 v230, v[136:139] offset:4160
	ds_write_b128 v230, v[140:143] offset:5184
	s_cbranch_vccnz .LBB0_1567
	v_lshl_add_u64 v[156:157], v[202:203], 2, s[4:5]
	global_store_dwordx4 v[156:157], v[136:139], off offset:2112
	global_store_dwordx4 v[156:157], v[140:143], off offset:3136
.LBB0_1567:
	s_or_b64 exec, exec, s[0:1]
	s_and_saveexec_b64 s[0:1], s[42:43]
	s_cbranch_execz .LBB0_1569
	v_pk_mul_f32 v[138:139], v[62:63], v[100:101] op_sel_hi:[1,0]
	v_pk_mul_f32 v[136:137], v[60:61], v[100:101] op_sel_hi:[1,0]
	v_lshl_add_u64 v[156:157], v[202:203], 2, s[4:5]
	v_pk_mul_f32 v[142:143], v[54:55], v[100:101] op_sel:[0,1]
	v_pk_mul_f32 v[140:141], v[52:53], v[100:101] op_sel:[0,1]
	global_store_dwordx4 v[156:157], v[136:139], off offset:64
	global_store_dwordx4 v[156:157], v[140:143], off offset:1088
.LBB0_1569:
	s_or_b64 exec, exec, s[0:1]
	s_and_saveexec_b64 s[0:1], s[12:13]
	s_cbranch_execz .LBB0_1572
	v_pk_mul_f32 v[138:139], v[114:115], v[102:103] op_sel_hi:[1,0]
	v_pk_mul_f32 v[136:137], v[112:113], v[102:103] op_sel_hi:[1,0]
	ds_write_b128 v230, v[136:139] offset:512
	v_pk_mul_f32 v[138:139], v[106:107], v[102:103] op_sel:[0,1]
	v_pk_mul_f32 v[136:137], v[104:105], v[102:103] op_sel:[0,1]
	ds_write_b128 v230, v[136:139] offset:1536
	v_pk_mul_f32 v[138:139], v[78:79], v[74:75] op_sel_hi:[1,0]
	v_pk_mul_f32 v[136:137], v[76:77], v[74:75] op_sel_hi:[1,0]
	v_pk_mul_f32 v[142:143], v[66:67], v[74:75] op_sel:[0,1]
	v_pk_mul_f32 v[140:141], v[64:65], v[74:75] op_sel:[0,1]
	s_and_b64 vcc, exec, s[8:9]
	ds_write_b128 v230, v[136:139] offset:4608
	ds_write_b128 v230, v[140:143] offset:5632
	s_cbranch_vccnz .LBB0_1572
	v_lshl_add_u64 v[156:157], v[202:203], 2, s[4:5]
	global_store_dwordx4 v[156:157], v[136:139], off offset:2560
	global_store_dwordx4 v[156:157], v[140:143], off offset:3584
.LBB0_1572:
	s_or_b64 exec, exec, s[0:1]
	s_and_saveexec_b64 s[0:1], s[42:43]
	s_cbranch_execz .LBB0_1574
	v_pk_mul_f32 v[138:139], v[130:131], v[100:101] op_sel_hi:[1,0]
	v_pk_mul_f32 v[136:137], v[128:129], v[100:101] op_sel_hi:[1,0]
	v_lshl_add_u64 v[156:157], v[202:203], 2, s[4:5]
	v_pk_mul_f32 v[142:143], v[122:123], v[100:101] op_sel:[0,1]
	v_pk_mul_f32 v[140:141], v[120:121], v[100:101] op_sel:[0,1]
	global_store_dwordx4 v[156:157], v[136:139], off offset:512
	global_store_dwordx4 v[156:157], v[140:143], off offset:1536
.LBB0_1574:
	s_or_b64 exec, exec, s[0:1]
	s_and_saveexec_b64 s[0:1], s[12:13]
	s_cbranch_execz .LBB0_1577
	v_pk_mul_f32 v[138:139], v[42:43], v[102:103] op_sel_hi:[1,0]
	v_pk_mul_f32 v[136:137], v[40:41], v[102:103] op_sel_hi:[1,0]
	ds_write_b128 v230, v[136:139] offset:576
	v_pk_mul_f32 v[138:139], v[34:35], v[102:103] op_sel:[0,1]
	v_pk_mul_f32 v[136:137], v[32:33], v[102:103] op_sel:[0,1]
	ds_write_b128 v230, v[136:139] offset:1600
	v_pk_mul_f32 v[138:139], v[10:11], v[74:75] op_sel_hi:[1,0]
	v_pk_mul_f32 v[136:137], v[8:9], v[74:75] op_sel_hi:[1,0]
	v_pk_mul_f32 v[142:143], v[2:3], v[74:75] op_sel:[0,1]
	v_pk_mul_f32 v[140:141], v[0:1], v[74:75] op_sel:[0,1]
	s_and_b64 vcc, exec, s[8:9]
	ds_write_b128 v230, v[136:139] offset:4672
	ds_write_b128 v230, v[140:143] offset:5696
	s_cbranch_vccnz .LBB0_1577
	v_lshl_add_u64 v[144:145], v[202:203], 2, s[4:5]
	global_store_dwordx4 v[144:145], v[136:139], off offset:2624
	global_store_dwordx4 v[144:145], v[140:143], off offset:3648
.LBB0_1577:
	s_or_b64 exec, exec, s[0:1]
	s_and_saveexec_b64 s[0:1], s[42:43]
	s_cbranch_execz .LBB0_1579
	v_pk_mul_f32 v[138:139], v[58:59], v[100:101] op_sel_hi:[1,0]
	v_pk_mul_f32 v[136:137], v[56:57], v[100:101] op_sel_hi:[1,0]
	v_lshl_add_u64 v[144:145], v[202:203], 2, s[4:5]
	v_pk_mul_f32 v[142:143], v[50:51], v[100:101] op_sel:[0,1]
	v_pk_mul_f32 v[140:141], v[48:49], v[100:101] op_sel:[0,1]
	global_store_dwordx4 v[144:145], v[136:139], off offset:576
	global_store_dwordx4 v[144:145], v[140:143], off offset:1600

;     __device__ __forceinline__ void run(const f32x4 (&acc)[2][2][4][2], const Unit& u, const Unit& nxt, bool has_next, int ui, int wr, int wc, int fr_in, int fq_in) const {
;     ...
;         for (int n = 0; n < 2; ++n) {
;             const int cl = wc * 32 + n * 16 + 4 * fq, ch = u.pn * 128 + cl;
;             const PG8_LAS float* pp = prm + slot * 1024 + cl;
;             const f32x4 wg0 = *(const PG8_LAS f32x4*)(pp), wg1 = *(const PG8_LAS f32x4*)(pp + 128), wg2 = *(const PG8_LAS f32x4*)(pp + 256), bg = *(const PG8_LAS f32x4*)(pp + 384);
;             const f32x4 wv0 = *(const PG8_LAS f32x4*)(pp + 512), wv1 = *(const PG8_LAS f32x4*)(pp + 640), wv2 = *(const PG8_LAS f32x4*)(pp + 768), bv = *(const PG8_LAS f32x4*)(pp + 896);
; #pragma unroll
;             for (int ai = 0; ai < 2; ++ai) {
;                 const int grp = 2 * ai + wr;
;                 f32x4 hg2 = {0.f, 0.f, 0.f, 0.f}, hg3 = hg2, hv2 = hg2, hv3 = hg2;
;                 if (grp > 0 && fr == 0) { const PG8_LAS float* xp = xr + ((grp - 1) * 2) * 256 + cl;
;                     hg2 = *(const PG8_LAS f32x4*)(xp); hg3 = *(const PG8_LAS f32x4*)(xp + 256); hv2 = *(const PG8_LAS f32x4*)(xp + 128); hv3 = *(const PG8_LAS f32x4*)(xp + 256 + 128); }
;                 f32x4 pg2, pg1, pv2, pv1;
;                 {
;                     const f32x4 g2 = acc[ai][0][2][n] * rs[ai][2], g3 = acc[ai][0][3][n] * rs[ai][3], v2 = acc[ai][1][2][n] * rs[ai][2], v3 = acc[ai][1][3][n] * rs[ai][3];
; #pragma unroll
;                     for (int i = 0; i < 4; ++i) {
;                         float a0 = g2[i], a1 = g3[i], a2 = v2[i], a3 = v3[i];
;                         asm volatile("" : "+v"(a0), "+v"(a1), "+v"(a2), "+v"(a3));
;                         const float t0 = DPPF(a0, 0x111), t1 = DPPF(a1, 0x111), t2 = DPPF(a2, 0x111), t3 = DPPF(a3, 0x111);
;                         pg2[i] = t0 + hg2[i]; pg1[i] = t1 + hg3[i]; pv2[i] = t2 + hv2[i]; pv1[i] = t3 + hv3[i]; }
;                 }
; #pragma unroll
;                 for (int m = 0; m < 4; ++m) {
;                     const f32x4 gc = acc[ai][0][m][n] * rs[ai][m], vc = acc[ai][1][m][n] * rs[ai][m];
;                     const f32x4 cgt = bg + wg0 * pg2 + wg1 * pg1 + wg2 * gc, cvl = bv + wv0 * pv2 + wv1 * pv1 + wv2 * vc;
;                     float a[4];
; #pragma unroll
;                     for (int i = 0; i < 4; ++i) a[i] = cgt[i] * sigmoidf_(cgt[i]) * cvl[i];
.LBB0_1585:
	s_or_b64 exec, exec, s[0:1]
	v_mul_f32_dpp v146, v44, v198 row_shr:1 row_mask:0xf bank_mask:0xf bound_ctrl:1
	s_nop 0
	v_mul_f32_dpp v152, v32, v199 row_shr:1 row_mask:0xf bank_mask:0xf bound_ctrl:1
	v_mul_f32_dpp v150, v40, v198 row_shr:1 row_mask:0xf bank_mask:0xf bound_ctrl:1
	v_mul_f32_dpp v148, v36, v199 row_shr:1 row_mask:0xf bank_mask:0xf bound_ctrl:1
	v_mul_f32_dpp v149, v37, v199 row_shr:1 row_mask:0xf bank_mask:0xf bound_ctrl:1
	v_mul_f32_dpp v147, v45, v198 row_shr:1 row_mask:0xf bank_mask:0xf bound_ctrl:1
	v_mul_f32_dpp v151, v41, v198 row_shr:1 row_mask:0xf bank_mask:0xf bound_ctrl:1
	v_mul_f32_dpp v153, v33, v199 row_shr:1 row_mask:0xf bank_mask:0xf bound_ctrl:1
	v_mul_f32_dpp v154, v46, v198 row_shr:1 row_mask:0xf bank_mask:0xf bound_ctrl:1
	v_mul_f32_dpp v160, v34, v199 row_shr:1 row_mask:0xf bank_mask:0xf bound_ctrl:1
	s_waitcnt lgkmcnt(0)
	v_pk_add_f32 v[118:119], v[118:119], v[146:147]
	v_mov_b32_e32 v140, v100
	v_mov_b32_e32 v141, v100
	v_mul_f32_dpp v158, v42, v198 row_shr:1 row_mask:0xf bank_mask:0xf bound_ctrl:1
	v_pk_add_f32 v[114:115], v[114:115], v[148:149]
	v_pk_fma_f32 v[118:119], v[84:85], v[118:119], v[96:97]
	v_mul_f32_dpp v157, v39, v199 row_shr:1 row_mask:0xf bank_mask:0xf bound_ctrl:1
	v_pk_mul_f32 v[60:61], v[60:61], v[100:101] op_sel_hi:[1,0]
	v_pk_fma_f32 v[118:119], v[88:89], v[114:115], v[118:119]
	v_mul_f32_dpp v159, v43, v198 row_shr:1 row_mask:0xf bank_mask:0xf bound_ctrl:1
	v_pk_fma_f32 v[118:119], v[60:61], v[92:93], v[118:119]
	v_mul_f32_dpp v156, v38, v199 row_shr:1 row_mask:0xf bank_mask:0xf bound_ctrl:1
	v_mul_f32_dpp v161, v35, v199 row_shr:1 row_mask:0xf bank_mask:0xf bound_ctrl:1
	v_mov_b32_e32 v162, v100
	v_mov_b32_e32 v163, v100
	v_mul_f32_dpp v155, v47, v198 row_shr:1 row_mask:0xf bank_mask:0xf bound_ctrl:1
	v_exp_f32_e32 v100, v118
	v_exp_f32_e32 v105, v119
	v_pk_mul_f32 v[140:141], v[56:57], v[140:141]
	v_add_f32_e32 v100, 1.0, v100
	v_rcp_f32_e32 v146, v100
	v_add_f32_e32 v100, 1.0, v105
	v_rcp_f32_e32 v147, v100
	v_pk_add_f32 v[56:57], v[110:111], v[150:151]
	v_pk_add_f32 v[116:117], v[116:117], v[156:157]
	v_pk_mul_f32 v[62:63], v[62:63], v[162:163]
	v_pk_mul_f32 v[110:111], v[118:119], v[146:147]
	v_pk_add_f32 v[118:119], v[120:121], v[154:155]
	v_pk_add_f32 v[106:107], v[106:107], v[152:153]
	v_pk_fma_f32 v[118:119], v[86:87], v[118:119], v[98:99]
	v_pk_fma_f32 v[56:57], v[64:65], v[56:57], v[80:81]
	v_pk_fma_f32 v[118:119], v[90:91], v[116:117], v[118:119]
	v_pk_fma_f32 v[56:57], v[68:69], v[106:107], v[56:57]
	v_pk_fma_f32 v[118:119], v[62:63], v[94:95], v[118:119]
	v_pk_fma_f32 v[56:57], v[140:141], v[76:77], v[56:57]
	v_exp_f32_e32 v100, v118
	v_exp_f32_e32 v105, v119
	v_pk_mul_f32 v[56:57], v[56:57], v[110:111]
	v_add_f32_e32 v100, 1.0, v100
	v_rcp_f32_e32 v120, v100
	v_add_f32_e32 v100, 1.0, v105
	v_rcp_f32_e32 v121, v100
	v_pk_add_f32 v[110:111], v[112:113], v[158:159]
	v_pk_add_f32 v[108:109], v[108:109], v[160:161]
	v_pk_fma_f32 v[110:111], v[66:67], v[110:111], v[82:83]
	v_add_u32_e32 v144, s12, v176
	v_pk_mul_f32 v[58:59], v[58:59], v[162:163]
	v_pk_fma_f32 v[110:111], v[70:71], v[108:109], v[110:111]
	v_ashrrev_i32_e32 v145, 31, v144
	v_pk_mul_f32 v[112:113], v[118:119], v[120:121]
	v_pk_fma_f32 v[110:111], v[58:59], v[78:79], v[110:111]
	v_mov_b32_e32 v142, v101
	v_pk_mul_f32 v[110:111], v[110:111], v[112:113]
	v_cvt_pk_bf16_f32 v112, v56, v57
	v_lshlrev_b64 v[56:57], 1, v[144:145]
	v_cvt_pk_bf16_f32 v113, v110, v111
	v_lshl_add_u64 v[110:111], v[128:129], 0, v[56:57]
	v_mov_b32_e32 v143, v101
	global_store_dwordx2 v[110:111], v[112:113], off
	v_pk_fma_f32 v[110:111], v[84:85], v[114:115], v[96:97]
	v_pk_mul_f32 v[52:53], v[52:53], v[142:143]
	v_pk_fma_f32 v[110:111], v[60:61], v[88:89], v[110:111]
	v_pk_fma_f32 v[106:107], v[64:65], v[106:107], v[80:81]
	v_pk_fma_f32 v[110:111], v[52:53], v[92:93], v[110:111]
	v_pk_mul_f32 v[48:49], v[48:49], v[142:143]
	v_exp_f32_e32 v105, v110
	v_exp_f32_e32 v113, v111
	v_mov_b32_e32 v100, v101
	v_add_f32_e32 v105, 1.0, v105
	v_rcp_f32_e32 v112, v105
	v_add_f32_e32 v105, 1.0, v113
	v_rcp_f32_e32 v113, v105
	v_pk_mul_f32 v[54:55], v[54:55], v[100:101]
	v_pk_mul_f32 v[50:51], v[50:51], v[100:101]
	v_pk_fma_f32 v[106:107], v[140:141], v[68:69], v[106:107]
	v_pk_mul_f32 v[100:101], v[110:111], v[112:113]
	v_pk_fma_f32 v[110:111], v[86:87], v[116:117], v[98:99]
	v_pk_fma_f32 v[108:109], v[66:67], v[108:109], v[82:83]
	v_pk_fma_f32 v[110:111], v[62:63], v[90:91], v[110:111]
	v_pk_fma_f32 v[106:107], v[48:49], v[76:77], v[106:107]
	v_pk_fma_f32 v[110:111], v[54:55], v[94:95], v[110:111]
	v_pk_fma_f32 v[108:109], v[58:59], v[70:71], v[108:109]
	v_exp_f32_e32 v105, v110
	v_exp_f32_e32 v113, v111
	v_mov_b32_e32 v138, v102
	v_add_f32_e32 v105, 1.0, v105
	v_rcp_f32_e32 v112, v105
	v_add_f32_e32 v105, 1.0, v113
	v_rcp_f32_e32 v113, v105
	v_mov_b32_e32 v139, v102
	v_pk_mul_f32 v[100:101], v[106:107], v[100:101]
	v_pk_fma_f32 v[108:109], v[50:51], v[78:79], v[108:109]
	v_pk_mul_f32 v[106:107], v[110:111], v[112:113]
	v_pk_fma_f32 v[60:61], v[60:61], v[84:85], v[96:97]
	v_pk_mul_f32 v[106:107], v[108:109], v[106:107]
	v_pk_mul_f32 v[44:45], v[44:45], v[138:139]
	v_pk_fma_f32 v[60:61], v[52:53], v[88:89], v[60:61]
	v_cvt_pk_bf16_f32 v100, v100, v101
	v_cvt_pk_bf16_f32 v101, v106, v107
	v_lshl_add_u64 v[106:107], v[126:127], 0, v[56:57]
	v_pk_fma_f32 v[60:61], v[44:45], v[92:93], v[60:61]
	v_mov_b32_e32 v136, v103
	v_mov_b32_e32 v137, v103
	global_store_dwordx2 v[106:107], v[100:101], off
	v_pk_fma_f32 v[52:53], v[52:53], v[84:85], v[96:97]
	v_exp_f32_e32 v105, v60
	v_pk_mul_f32 v[36:37], v[36:37], v[102:103] op_sel:[0,1]
;     __device__ __forceinline__ void run(const f32x4 (&acc)[2][2][4][2], const Unit& u, const Unit& nxt, bool has_next, int ui, int wr, int wc, int fr_in, int fq_in) const {
;     ...
;         for (int n = 0; n < 2; ++n) {
;             const int cl = wc * 32 + n * 16 + 4 * fq, ch = u.pn * 128 + cl;
;             const PG8_LAS float* pp = prm + slot * 1024 + cl;
;             const f32x4 wg0 = *(const PG8_LAS f32x4*)(pp), wg1 = *(const PG8_LAS f32x4*)(pp + 128), wg2 = *(const PG8_LAS f32x4*)(pp + 256), bg = *(const PG8_LAS f32x4*)(pp + 384);
;             const f32x4 wv0 = *(const PG8_LAS f32x4*)(pp + 512), wv1 = *(const PG8_LAS f32x4*)(pp + 640), wv2 = *(const PG8_LAS f32x4*)(pp + 768), bv = *(const PG8_LAS f32x4*)(pp + 896);
; #pragma unroll
;             for (int ai = 0; ai < 2; ++ai) {
;                 const int grp = 2 * ai + wr;
;                 f32x4 hg2 = {0.f, 0.f, 0.f, 0.f}, hg3 = hg2, hv2 = hg2, hv3 = hg2;
;                 if (grp > 0 && fr == 0) { const PG8_LAS float* xp = xr + ((grp - 1) * 2) * 256 + cl;
;                     hg2 = *(const PG8_LAS f32x4*)(xp); hg3 = *(const PG8_LAS f32x4*)(xp + 256); hv2 = *(const PG8_LAS f32x4*)(xp + 128); hv3 = *(const PG8_LAS f32x4*)(xp + 256 + 128); }
;                 f32x4 pg2, pg1, pv2, pv1;
;                 {
;                     const f32x4 g2 = acc[ai][0][2][n] * rs[ai][2], g3 = acc[ai][0][3][n] * rs[ai][3], v2 = acc[ai][1][2][n] * rs[ai][2], v3 = acc[ai][1][3][n] * rs[ai][3];
; #pragma unroll
;                     for (int i = 0; i < 4; ++i) {
;                         float a0 = g2[i], a1 = g3[i], a2 = v2[i], a3 = v3[i];
;                         asm volatile("" : "+v"(a0), "+v"(a1), "+v"(a2), "+v"(a3));
;                         const float t0 = DPPF(a0, 0x111), t1 = DPPF(a1, 0x111), t2 = DPPF(a2, 0x111), t3 = DPPF(a3, 0x111);
;                         pg2[i] = t0 + hg2[i]; pg1[i] = t1 + hg3[i]; pv2[i] = t2 + hv2[i]; pv1[i] = t3 + hv3[i]; }
;                 }
; #pragma unroll
;                 for (int m = 0; m < 4; ++m) {
;                     const f32x4 gc = acc[ai][0][m][n] * rs[ai][m], vc = acc[ai][1][m][n] * rs[ai][m];
;                     const f32x4 cgt = bg + wg0 * pg2 + wg1 * pg1 + wg2 * gc, cvl = bv + wv0 * pv2 + wv1 * pv1 + wv2 * vc;
;                     float a[4];
; #pragma unroll
;                     for (int i = 0; i < 4; ++i) a[i] = cgt[i] * sigmoidf_(cgt[i]) * cvl[i];
	v_pk_fma_f32 v[44:45], v[44:45], v[88:89], v[52:53]
	v_exp_f32_e32 v107, v61
	v_pk_fma_f32 v[36:37], v[36:37], v[92:93], v[44:45]
	v_mov_b32_e32 v100, v102
	v_mov_b32_e32 v101, v102
	v_pk_fma_f32 v[62:63], v[62:63], v[86:87], v[98:99]
	v_pk_mul_f32 v[46:47], v[46:47], v[102:103] op_sel_hi:[1,0]
	v_pk_fma_f32 v[62:63], v[54:55], v[90:91], v[62:63]
	v_exp_f32_e32 v44, v36
	v_exp_f32_e32 v45, v37
	v_add_f32_e32 v102, 1.0, v105
	v_pk_fma_f32 v[62:63], v[46:47], v[94:95], v[62:63]
	v_rcp_f32_e32 v106, v102
	v_add_f32_e32 v102, 1.0, v107
	v_pk_mul_f32 v[42:43], v[42:43], v[100:101]
	v_rcp_f32_e32 v107, v102
	v_exp_f32_e32 v102, v62
	v_exp_f32_e32 v105, v63
	v_add_f32_e32 v44, 1.0, v44
	v_add_f32_e32 v45, 1.0, v45
	v_rcp_f32_e32 v44, v44
	v_rcp_f32_e32 v45, v45
	v_add_f32_e32 v102, 1.0, v102
	v_pk_mul_f32 v[60:61], v[60:61], v[106:107]
	v_rcp_f32_e32 v106, v102
	v_add_f32_e32 v102, 1.0, v105
	v_rcp_f32_e32 v107, v102
	v_mov_b32_e32 v102, v103
	v_pk_mul_f32 v[36:37], v[36:37], v[44:45]
	v_pk_fma_f32 v[44:45], v[54:55], v[86:87], v[98:99]
	v_pk_mul_f32 v[38:39], v[38:39], v[102:103]
	v_pk_fma_f32 v[44:45], v[46:47], v[90:91], v[44:45]
	v_pk_fma_f32 v[100:101], v[140:141], v[64:65], v[80:81]
	v_pk_fma_f32 v[38:39], v[38:39], v[94:95], v[44:45]
	v_pk_mul_f32 v[40:41], v[40:41], v[138:139]
	v_exp_f32_e32 v46, v38
	v_exp_f32_e32 v47, v39
	v_pk_fma_f32 v[100:101], v[48:49], v[68:69], v[100:101]
	v_add_f32_e32 v46, 1.0, v46
	v_rcp_f32_e32 v46, v46
	v_add_f32_e32 v47, 1.0, v47
	v_rcp_f32_e32 v47, v47
	v_pk_fma_f32 v[44:45], v[48:49], v[64:65], v[80:81]
	v_pk_fma_f32 v[100:101], v[40:41], v[76:77], v[100:101]
	v_pk_mul_f32 v[32:33], v[32:33], v[102:103] op_sel:[0,1]
	v_pk_fma_f32 v[40:41], v[40:41], v[68:69], v[44:45]
	v_pk_fma_f32 v[58:59], v[58:59], v[66:67], v[82:83]
	v_pk_fma_f32 v[32:33], v[32:33], v[76:77], v[40:41]
	v_pk_fma_f32 v[58:59], v[50:51], v[70:71], v[58:59]
	v_pk_mul_f32 v[32:33], v[32:33], v[36:37]
	v_pk_mul_f32 v[36:37], v[38:39], v[46:47]
	v_pk_fma_f32 v[38:39], v[50:51], v[66:67], v[82:83]
	v_pk_mul_f32 v[34:35], v[34:35], v[102:103]
	v_pk_fma_f32 v[38:39], v[42:43], v[70:71], v[38:39]
	v_pk_mul_f32 v[62:63], v[62:63], v[106:107]
	v_pk_fma_f32 v[58:59], v[42:43], v[78:79], v[58:59]
	v_pk_fma_f32 v[34:35], v[34:35], v[78:79], v[38:39]
	v_pk_mul_f32 v[60:61], v[100:101], v[60:61]
	v_pk_mul_f32 v[58:59], v[58:59], v[62:63]
	v_pk_mul_f32 v[34:35], v[34:35], v[36:37]
	v_cvt_pk_bf16_f32 v60, v60, v61
	v_cvt_pk_bf16_f32 v61, v58, v59
	v_lshl_add_u64 v[58:59], v[132:133], 0, v[56:57]
	v_cvt_pk_bf16_f32 v32, v32, v33
	v_cvt_pk_bf16_f32 v33, v34, v35
	v_lshl_add_u64 v[34:35], v[172:173], 0, v[56:57]
	global_store_dwordx2 v[58:59], v[60:61], off
	global_store_dwordx2 v[34:35], v[32:33], off
	v_mov_b32_e32 v105, 0
	v_mov_b32_e32 v106, 0
	v_mov_b32_e32 v107, 0
	v_mov_b32_e32 v32, 0
	v_mov_b32_e32 v33, 0
	v_mov_b32_e32 v34, 0
	v_mov_b32_e32 v35, 0
	v_mov_b32_e32 v36, 0
	v_mov_b32_e32 v37, 0
	v_mov_b32_e32 v38, 0
	v_mov_b32_e32 v39, 0
	v_mov_b32_e32 v40, 0
	v_mov_b32_e32 v41, 0
	v_mov_b32_e32 v42, 0
	v_mov_b32_e32 v43, 0
	s_and_saveexec_b64 s[0:1], s[10:11]
	s_cbranch_execz .LBB0_1587
	ds_read_b128 v[40:43], v230 offset:2112
	ds_read_b128 v[32:35], v230 offset:2624
	ds_read_b128 v[36:39], v230 offset:3136
	ds_read_b128 v[104:107], v230 offset:3648
.LBB0_1587:
	s_or_b64 exec, exec, s[0:1]
	v_mul_f32_dpp v54, v4, v201 row_shr:1 row_mask:0xf bank_mask:0xf bound_ctrl:1
	v_mul_f32_dpp v58, v8, v200 row_shr:1 row_mask:0xf bank_mask:0xf bound_ctrl:1
	v_mul_f32_dpp v60, v0, v201 row_shr:1 row_mask:0xf bank_mask:0xf bound_ctrl:1
	v_mul_f32_dpp v52, v12, v200 row_shr:1 row_mask:0xf bank_mask:0xf bound_ctrl:1
	v_mul_f32_dpp v53, v13, v200 row_shr:1 row_mask:0xf bank_mask:0xf bound_ctrl:1
	s_waitcnt lgkmcnt(0)
	v_pk_add_f32 v[40:41], v[40:41], v[52:53]
	v_pk_mul_f32 v[28:29], v[28:29], v[72:73] op_sel_hi:[1,0]
	v_mul_f32_dpp v55, v5, v201 row_shr:1 row_mask:0xf bank_mask:0xf bound_ctrl:1
	v_pk_add_f32 v[36:37], v[36:37], v[54:55]
	v_pk_fma_f32 v[40:41], v[84:85], v[40:41], v[96:97]
	v_pk_fma_f32 v[40:41], v[88:89], v[36:37], v[40:41]
	v_pk_fma_f32 v[40:41], v[28:29], v[92:93], v[40:41]
	v_mul_f32_dpp v59, v9, v200 row_shr:1 row_mask:0xf bank_mask:0xf bound_ctrl:1
	v_exp_f32_e32 v52, v40
	v_exp_f32_e32 v53, v41
	v_mul_f32_dpp v61, v1, v201 row_shr:1 row_mask:0xf bank_mask:0xf bound_ctrl:1
	v_mul_f32_dpp v100, v6, v201 row_shr:1 row_mask:0xf bank_mask:0xf bound_ctrl:1
	v_mul_f32_dpp v102, v10, v200 row_shr:1 row_mask:0xf bank_mask:0xf bound_ctrl:1
	v_mul_f32_dpp v108, v2, v201 row_shr:1 row_mask:0xf bank_mask:0xf bound_ctrl:1
	v_mul_f32_dpp v62, v14, v200 row_shr:1 row_mask:0xf bank_mask:0xf bound_ctrl:1
	v_add_f32_e32 v52, 1.0, v52
	v_add_f32_e32 v53, 1.0, v53
	v_mul_f32_dpp v63, v15, v200 row_shr:1 row_mask:0xf bank_mask:0xf bound_ctrl:1
	v_rcp_f32_e32 v52, v52
	v_rcp_f32_e32 v53, v53
	v_mul_f32_dpp v101, v7, v201 row_shr:1 row_mask:0xf bank_mask:0xf bound_ctrl:1
	v_pk_add_f32 v[42:43], v[42:43], v[62:63]
	v_mov_b32_e32 v111, v72
	v_mul_f32_dpp v103, v11, v200 row_shr:1 row_mask:0xf bank_mask:0xf bound_ctrl:1
	v_pk_add_f32 v[38:39], v[38:39], v[100:101]
	v_pk_fma_f32 v[42:43], v[86:87], v[42:43], v[98:99]
	v_mul_f32_dpp v109, v3, v201 row_shr:1 row_mask:0xf bank_mask:0xf bound_ctrl:1
	v_mov_b32_e32 v110, v72
	v_pk_mul_f32 v[30:31], v[30:31], v[110:111]
	v_pk_fma_f32 v[42:43], v[90:91], v[38:39], v[42:43]
	v_pk_mul_f32 v[40:41], v[40:41], v[52:53]
	v_pk_fma_f32 v[42:43], v[30:31], v[94:95], v[42:43]
	v_pk_add_f32 v[32:33], v[32:33], v[58:59]
	v_exp_f32_e32 v52, v42
	v_exp_f32_e32 v53, v43
	v_pk_mul_f32 v[24:25], v[24:25], v[72:73] op_sel_hi:[1,0]
; __device__ __forceinline__ unsigned pk2(float lo, float hi) { f32x2_t v = {lo, hi}; bf16x2_t b = __builtin_convertvector(v, bf16x2_t); return __builtin_bit_cast(unsigned, b); }
; #define DPPF(v, ctrl) __builtin_bit_cast(float, __builtin_amdgcn_update_dpp(0, __builtin_bit_cast(int, (v)), (ctrl), 0xf, 0xf, false))
; __device__ __forceinline__ float fast_rsq(float x) { return __builtin_amdgcn_rsqf(x); }
; __device__ __forceinline__ float sigmoidf_(float v) { return fast_rcp(1.0f + fast_exp2(-v * LOG2E)); }
;     __device__ __forceinline__ void run(const f32x4 (&acc)[2][2][4][2], const Unit& u, const Unit& nxt, bool has_next, int ui, int wr, int wc, int fr_in, int fq_in) const {
;     ...
;                     const f32x4 g2 = acc[ai][0][2][n] * rs[ai][2], g3 = acc[ai][0][3][n] * rs[ai][3], v2 = acc[ai][1][2][n] * rs[ai][2], v3 = acc[ai][1][3][n] * rs[ai][3];
; #pragma unroll
;                     for (int i = 0; i < 4; ++i) {
;                         float a0 = g2[i], a1 = g3[i], a2 = v2[i], a3 = v3[i];
;                         asm volatile("" : "+v"(a0), "+v"(a1), "+v"(a2), "+v"(a3));
;                         const float t0 = DPPF(a0, 0x111), t1 = DPPF(a1, 0x111), t2 = DPPF(a2, 0x111), t3 = DPPF(a3, 0x111);
;                         pg2[i] = t0 + hg2[i]; pg1[i] = t1 + hg3[i]; pv2[i] = t2 + hv2[i]; pv1[i] = t3 + hv3[i]; }
;                 }
; #pragma unroll
;                 for (int m = 0; m < 4; ++m) {
;                     const f32x4 gc = acc[ai][0][m][n] * rs[ai][m], vc = acc[ai][1][m][n] * rs[ai][m];
;                     const f32x4 cgt = bg + wg0 * pg2 + wg1 * pg1 + wg2 * gc, cvl = bv + wv0 * pv2 + wv1 * pv1 + wv2 * vc;
;                     float a[4];
; #pragma unroll
;                     for (int i = 0; i < 4; ++i) a[i] = cgt[i] * sigmoidf_(cgt[i]) * cvl[i];
;                     u32x2 w; w.x = pk2(a[0], a[1]); w.y = pk2(a[2], a[3]);
;                     *(u32x2*)(A + (size_t)(u.pm * BM + ai * 128 + wr * 64 + 4 * fr + m) * DFF + ch) = w;
;                     pg2 = pg1; pg1 = gc; pv2 = pv1; pv1 = vc;
;                 }
;                 asm volatile("" ::: "memory");
;             }
;         }
;         if (has_next) {
;             prm[(slot ^ 1) * 1024 + tid] = nx0; prm[(slot ^ 1) * 1024 + tid + 512] = nx1;
;             if (tid < 256) rsd[(slot ^ 1) * 256 + tid] = fast_rsq(nrs * (1.0f / DM) + EPS);
;         }
	v_pk_add_f32 v[48:49], v[104:105], v[60:61]
	v_pk_fma_f32 v[32:33], v[64:65], v[32:33], v[80:81]
	v_add_f32_e32 v52, 1.0, v52
	v_add_f32_e32 v53, 1.0, v53
	v_pk_fma_f32 v[32:33], v[68:69], v[48:49], v[32:33]
	v_rcp_f32_e32 v52, v52
	v_rcp_f32_e32 v53, v53
	v_pk_fma_f32 v[32:33], v[24:25], v[76:77], v[32:33]
	v_pk_add_f32 v[34:35], v[34:35], v[102:103]
	v_pk_mul_f32 v[32:33], v[32:33], v[40:41]
	v_pk_add_f32 v[40:41], v[106:107], v[108:109]
	v_pk_fma_f32 v[34:35], v[66:67], v[34:35], v[82:83]
	v_pk_mul_f32 v[26:27], v[26:27], v[110:111]
	v_pk_fma_f32 v[34:35], v[70:71], v[40:41], v[34:35]
	v_pk_mul_f32 v[42:43], v[42:43], v[52:53]
	v_pk_fma_f32 v[34:35], v[26:27], v[78:79], v[34:35]
	v_cvt_pk_bf16_f32 v32, v32, v33
	v_pk_mul_f32 v[34:35], v[34:35], v[42:43]
	v_mov_b32_e32 v50, v73
	v_cvt_pk_bf16_f32 v33, v34, v35
	v_lshl_add_u64 v[34:35], v[122:123], 0, v[56:57]
	v_mov_b32_e32 v51, v73
	global_store_dwordx2 v[34:35], v[32:33], off
	v_pk_fma_f32 v[32:33], v[84:85], v[36:37], v[96:97]
	v_pk_mul_f32 v[20:21], v[20:21], v[50:51]
	v_pk_fma_f32 v[32:33], v[28:29], v[88:89], v[32:33]
	v_mov_b32_e32 v72, v73
	v_pk_fma_f32 v[32:33], v[20:21], v[92:93], v[32:33]
	v_pk_mul_f32 v[22:23], v[22:23], v[72:73]
	v_exp_f32_e32 v34, v32
	v_exp_f32_e32 v35, v33
	v_mov_b32_e32 v46, v74
	v_mov_b32_e32 v47, v74
	v_add_f32_e32 v34, 1.0, v34
	v_add_f32_e32 v35, 1.0, v35
	v_rcp_f32_e32 v34, v34
	v_rcp_f32_e32 v35, v35
	v_pk_fma_f32 v[28:29], v[28:29], v[84:85], v[96:97]
	v_mov_b32_e32 v44, v75
	v_mov_b32_e32 v45, v75
	v_pk_mul_f32 v[32:33], v[32:33], v[34:35]
	v_pk_fma_f32 v[34:35], v[86:87], v[38:39], v[98:99]
	v_pk_mul_f32 v[12:13], v[12:13], v[74:75] op_sel_hi:[1,0]
	v_pk_fma_f32 v[34:35], v[30:31], v[90:91], v[34:35]
	v_pk_fma_f32 v[28:29], v[20:21], v[88:89], v[28:29]
	v_pk_fma_f32 v[34:35], v[22:23], v[94:95], v[34:35]
	v_pk_fma_f32 v[20:21], v[20:21], v[84:85], v[96:97]
	v_exp_f32_e32 v38, v34
	v_exp_f32_e32 v39, v35
	v_pk_fma_f32 v[28:29], v[12:13], v[92:93], v[28:29]
	v_pk_mul_f32 v[4:5], v[4:5], v[74:75] op_sel:[0,1]
	v_pk_fma_f32 v[12:13], v[12:13], v[88:89], v[20:21]
	v_pk_fma_f32 v[36:37], v[64:65], v[48:49], v[80:81]
	v_add_f32_e32 v38, 1.0, v38
	v_add_f32_e32 v39, 1.0, v39
	v_pk_fma_f32 v[4:5], v[4:5], v[92:93], v[12:13]
	v_pk_mul_f32 v[16:17], v[16:17], v[50:51]
	v_rcp_f32_e32 v38, v38
	v_rcp_f32_e32 v39, v39
	v_pk_fma_f32 v[36:37], v[24:25], v[68:69], v[36:37]
	v_pk_fma_f32 v[36:37], v[16:17], v[76:77], v[36:37]
	v_exp_f32_e32 v12, v4
	v_exp_f32_e32 v13, v5
	v_pk_mul_f32 v[32:33], v[36:37], v[32:33]
	v_pk_fma_f32 v[36:37], v[66:67], v[40:41], v[82:83]
	v_pk_mul_f32 v[18:19], v[18:19], v[72:73]
	v_pk_fma_f32 v[36:37], v[26:27], v[70:71], v[36:37]
	v_pk_mul_f32 v[34:35], v[34:35], v[38:39]
	v_pk_fma_f32 v[36:37], v[18:19], v[78:79], v[36:37]
	v_add_f32_e32 v12, 1.0, v12
	v_pk_mul_f32 v[34:35], v[36:37], v[34:35]
	v_add_f32_e32 v13, 1.0, v13
	v_cvt_pk_bf16_f32 v32, v32, v33
	v_cvt_pk_bf16_f32 v33, v34, v35
	v_lshl_add_u64 v[34:35], v[124:125], 0, v[56:57]
	v_rcp_f32_e32 v12, v12
	v_rcp_f32_e32 v13, v13
	global_store_dwordx2 v[34:35], v[32:33], off
	v_exp_f32_e32 v34, v28
	v_mov_b32_e32 v32, v74
	v_exp_f32_e32 v35, v29
	v_mov_b32_e32 v33, v74
	v_pk_mul_f32 v[14:15], v[14:15], v[32:33]
	v_mov_b32_e32 v74, v75
	v_pk_mul_f32 v[4:5], v[4:5], v[12:13]
	v_pk_fma_f32 v[12:13], v[22:23], v[86:87], v[98:99]
	v_pk_mul_f32 v[6:7], v[6:7], v[74:75]
	v_pk_fma_f32 v[12:13], v[14:15], v[90:91], v[12:13]
	v_pk_fma_f32 v[30:31], v[30:31], v[86:87], v[98:99]
	v_pk_fma_f32 v[6:7], v[6:7], v[94:95], v[12:13]
	v_pk_fma_f32 v[30:31], v[22:23], v[90:91], v[30:31]
	v_pk_fma_f32 v[30:31], v[14:15], v[94:95], v[30:31]
	v_exp_f32_e32 v14, v6
	v_exp_f32_e32 v15, v7
	v_pk_mul_f32 v[10:11], v[10:11], v[32:33]
	v_exp_f32_e32 v32, v30
	v_exp_f32_e32 v33, v31
	v_add_f32_e32 v14, 1.0, v14
	v_add_f32_e32 v15, 1.0, v15
	v_add_f32_e32 v34, 1.0, v34
	v_add_f32_e32 v35, 1.0, v35
	v_pk_fma_f32 v[24:25], v[24:25], v[64:65], v[80:81]
	v_rcp_f32_e32 v14, v14
	v_rcp_f32_e32 v15, v15
	v_rcp_f32_e32 v34, v34
	v_rcp_f32_e32 v35, v35
	v_pk_mul_f32 v[8:9], v[8:9], v[46:47]
	v_add_f32_e32 v32, 1.0, v32
	v_add_f32_e32 v33, 1.0, v33
	v_pk_fma_f32 v[24:25], v[16:17], v[68:69], v[24:25]
	v_pk_fma_f32 v[12:13], v[16:17], v[64:65], v[80:81]
	v_rcp_f32_e32 v32, v32
	v_rcp_f32_e32 v33, v33
	v_pk_fma_f32 v[24:25], v[8:9], v[76:77], v[24:25]
	v_pk_mul_f32 v[0:1], v[0:1], v[74:75] op_sel:[0,1]
	v_pk_fma_f32 v[8:9], v[8:9], v[68:69], v[12:13]
	v_pk_fma_f32 v[26:27], v[26:27], v[66:67], v[82:83]
	v_pk_fma_f32 v[0:1], v[0:1], v[76:77], v[8:9]
	v_pk_mul_f32 v[28:29], v[28:29], v[34:35]
	v_pk_mul_f32 v[0:1], v[0:1], v[4:5]
	v_pk_mul_f32 v[4:5], v[6:7], v[14:15]
	v_pk_fma_f32 v[6:7], v[18:19], v[66:67], v[82:83]
	v_pk_fma_f32 v[26:27], v[18:19], v[70:71], v[26:27]
	v_pk_mul_f32 v[2:3], v[2:3], v[74:75]
	v_pk_fma_f32 v[6:7], v[10:11], v[70:71], v[6:7]
	v_pk_mul_f32 v[24:25], v[24:25], v[28:29]
	v_pk_mul_f32 v[28:29], v[30:31], v[32:33]
	v_pk_fma_f32 v[26:27], v[10:11], v[78:79], v[26:27]
	v_pk_fma_f32 v[2:3], v[2:3], v[78:79], v[6:7]
	v_pk_mul_f32 v[26:27], v[26:27], v[28:29]
	v_pk_mul_f32 v[2:3], v[2:3], v[4:5]
	v_cvt_pk_bf16_f32 v24, v24, v25
	v_cvt_pk_bf16_f32 v25, v26, v27
	v_lshl_add_u64 v[26:27], v[130:131], 0, v[56:57]
	v_cvt_pk_bf16_f32 v0, v0, v1
	v_cvt_pk_bf16_f32 v1, v2, v3
	v_lshl_add_u64 v[2:3], v[134:135], 0, v[56:57]
	global_store_dwordx2 v[26:27], v[24:25], off
	global_store_dwordx2 v[2:3], v[0:1], off
	s_and_b64 vcc, exec, s[6:7]
	s_mov_b64 s[0:1], -1
	s_cbranch_vccnz .LBB0_1543
	s_xor_b32 s4, s29, 0x400
	v_lshlrev_b32_e32 v0, 2, v226
	v_lshl_add_u32 v0, s4, 2, v0
	v_add_u32_e32 v0, 0x22040, v0
	v_cmp_gt_i32_e32 vcc, s33, v226
	s_waitcnt vmcnt(0)
	v_mul_f32_e32 v228, 0xbfb8aa3b, v228
	v_mul_f32_e32 v227, 0xbf317218, v227
	ds_write2st64_b32 v0, v228, v227 offset1:8
	s_and_saveexec_b64 s[0:1], vcc
	s_cbranch_execz .LBB0_1590
	v_rsq_f32_e32 v0, v229
	v_lshl_add_u32 v1, v226, 2, s4
	v_add_u32_e32 v1, 0x24040, v1
	ds_write_b32 v1, v0
